# phase10 GEMM epilogue: rolling prefetch of rstd2/E/h 8 groups ahead + DPP row-sum; phase0 rmsnorm jobs software-pipelined with hoisted gain
# speedup vs baseline: 1.2240x; 1.0113x over previous
.LBB0_17:
	v_writelane_b32 v242, s80, 17
	s_cmp_lt_i32 s92, 1
	s_cselect_b64 s[0:1], -1, 0
	v_writelane_b32 v242, s81, 18
	v_writelane_b32 v242, s82, 19
	v_writelane_b32 v242, s83, 20
	v_writelane_b32 v242, s84, 21
	v_writelane_b32 v242, s85, 22
	v_writelane_b32 v242, s86, 23
	v_writelane_b32 v242, s87, 24
	s_cmp_gt_i32 s93, 0
	v_writelane_b32 v242, s88, 25
	s_cselect_b64 s[4:5], -1, 0
	s_and_b64 s[0:1], s[0:1], s[4:5]
	v_writelane_b32 v242, s89, 26
	v_writelane_b32 v242, s90, 27
	v_writelane_b32 v242, s91, 28
	v_writelane_b32 v242, s92, 29
	v_writelane_b32 v242, s93, 30
	s_andn2_b64 vcc, exec, s[0:1]
	v_writelane_b32 v242, s94, 31
	v_writelane_b32 v242, s95, 32
	s_cbranch_vccnz .LBB0_115
	s_cmpk_gt_i32 s2, 0x15af
	s_cbranch_scc1 .LBB0_61
	v_readlane_b32 s80, v242, 1
	v_lshrrev_b32_e32 v1, 6, v218
	v_mov_b32_e32 v2, 0x1860
	s_movk_i32 s3, 0x104
	v_readlane_b32 s81, v242, 2
	s_add_u32 s0, s80, 0x542a000
	v_readlane_b32 s4, v243, 49
	v_and_b32_e32 v0, 63, v218
	v_mad_u32_u24 v37, v1, s3, v2
	v_lshlrev_b32_e32 v2, 2, v1
	s_addc_u32 s1, s81, 0
	v_readlane_b32 s8, v243, 53
	v_readlane_b32 s9, v243, 54
	v_readlane_b32 s10, v243, 55
	v_readlane_b32 s11, v243, 56
	v_readlane_b32 s12, v243, 57
	v_readlane_b32 s13, v243, 58
	v_readlane_b32 s14, v243, 59
	v_readlane_b32 s15, v243, 60
	v_readlane_b32 s16, v243, 61
	v_readlane_b32 s17, v243, 62
	v_readlane_b32 s18, v243, 63
	v_readlane_b32 s19, v242, 0
	v_mad_u32_u24 v76, v0, s3, v2
	v_mov_b32_e32 v3, 0
	v_lshlrev_b32_e32 v2, 2, v0
	v_readlane_b32 s36, v243, 17
	s_cmp_lg_u64 s[12:13], 0
	v_readlane_b32 s48, v243, 29
	v_readlane_b32 s49, v243, 30
	v_readlane_b32 s50, v243, 31
	v_readlane_b32 s51, v243, 32
	v_lshl_add_u64 v[12:13], s[14:15], 0, v[2:3]
	v_lshl_add_u64 v[16:17], s[16:17], 0, v[2:3]
	v_readlane_b32 s8, v243, 33
	v_mul_u32_u24_e32 v38, 0x104, v1
	v_readlane_b32 s37, v243, 18
	v_readlane_b32 s42, v243, 23
	v_readlane_b32 s43, v243, 24
	v_readlane_b32 s46, v243, 27
	v_readlane_b32 s47, v243, 28
	v_lshl_add_u64 v[4:5], s[48:49], 0, v[2:3]
	v_readlane_b32 s48, v243, 0
	v_readlane_b32 s20, v243, 45
	v_readlane_b32 s21, v243, 46
	v_readlane_b32 s82, v242, 3
	v_readlane_b32 s83, v242, 4
	v_readlane_b32 s84, v242, 5
	v_readlane_b32 s85, v242, 6
	v_readlane_b32 s86, v242, 7
	v_readlane_b32 s87, v242, 8
	v_readlane_b32 s88, v242, 9
	v_readlane_b32 s89, v242, 10
	v_readlane_b32 s90, v242, 11
	v_readlane_b32 s91, v242, 12
	v_readlane_b32 s92, v242, 13
	v_readlane_b32 s93, v242, 14
	v_readlane_b32 s94, v242, 15
	v_readlane_b32 s95, v242, 16
	v_lshlrev_b32_e32 v32, 1, v0
	v_mov_b32_e32 v33, v3
	v_readlane_b32 s49, v243, 1
	v_lshl_add_u64 v[8:9], s[46:47], 0, v[2:3]
	v_lshl_add_u64 v[10:11], s[42:43], 0, v[2:3]
	v_lshl_add_u64 v[20:21], s[20:21], 0, v[2:3]
	v_lshl_add_u64 v[24:25], s[36:37], 0, v[2:3]
	v_add_u32_e32 v94, v2, v38
	v_add_u32_e32 v95, v2, v37
	v_lshlrev_b32_e32 v40, 2, v2
	v_mbcnt_lo_u32_b32 v2, -1, 0
	v_lshlrev_b32_e32 v36, 2, v218
	v_add_u32_e32 v77, 4, v1
	v_add_u32_e32 v78, 8, v1
	v_add_u32_e32 v79, 12, v1
	v_or_b32_e32 v80, 16, v1
	v_add_u32_e32 v81, 20, v1
	v_add_u32_e32 v82, 24, v1
	v_add_u32_e32 v83, 28, v1
	v_or_b32_e32 v84, 32, v1
	v_add_u32_e32 v85, 36, v1
	v_add_u32_e32 v86, 40, v1
	v_add_u32_e32 v87, 44, v1
	v_or_b32_e32 v88, 48, v1
	v_add_u32_e32 v89, 52, v1
	v_add_u32_e32 v90, 56, v1
	v_add_u32_e32 v91, 60, v1
	v_lshl_add_u64 v[6:7], s[48:49], 0, v[32:33]
	v_lshl_add_u64 v[14:15], s[90:91], 0, v[32:33]
	v_lshl_add_u64 v[18:19], s[88:89], 0, v[32:33]
	v_lshl_add_u64 v[22:23], s[84:85], 0, v[32:33]
	v_lshl_add_u64 v[26:27], s[82:83], 0, v[32:33]
	v_readlane_b32 s80, v242, 17
	v_lshl_add_u64 v[30:31], s[94:95], 0, v[32:33]
	v_lshl_add_u64 v[32:33], s[92:93], 0, v[32:33]
	v_readlane_b32 s88, v242, 25
	v_mbcnt_hi_u32_b32 v97, -1, v2
	v_readlane_b32 s5, v243, 50
	v_readlane_b32 s7, v243, 52
	v_lshlrev_b32_e32 v42, 9, v1
	v_lshlrev_b32_e32 v44, 9, v77
	v_lshlrev_b32_e32 v46, 9, v78
	v_lshlrev_b32_e32 v48, 9, v79
	v_lshlrev_b32_e32 v50, 9, v80
	v_lshlrev_b32_e32 v52, 9, v81
	v_lshlrev_b32_e32 v54, 9, v82
	v_lshlrev_b32_e32 v56, 9, v83
	v_lshlrev_b32_e32 v58, 9, v84
	v_lshlrev_b32_e32 v60, 9, v85
	v_lshlrev_b32_e32 v62, 9, v86
	v_lshlrev_b32_e32 v64, 9, v87
	v_lshlrev_b32_e32 v66, 9, v88
	v_lshlrev_b32_e32 v68, 9, v89
	v_lshlrev_b32_e32 v70, 9, v90
	v_lshlrev_b32_e32 v72, 9, v91
	v_readlane_b32 s10, v243, 35
	v_readlane_b32 s11, v243, 36
	v_readlane_b32 s82, v242, 19
	v_readlane_b32 s83, v242, 20
	v_lshlrev_b32_e32 v28, 3, v0
	v_mov_b32_e32 v29, v3
	v_readlane_b32 s94, v242, 31
	v_lshlrev_b32_e32 v34, 4, v0
	v_mov_b32_e32 v35, v3
	v_lshl_add_u32 v36, s2, 10, v36
	v_and_b32_e32 v2, 64, v97
	s_cselect_b64 s[4:5], -1, 0
	v_readlane_b32 s81, v242, 18
	v_readlane_b32 s84, v242, 21
	v_readlane_b32 s85, v242, 22
	v_readlane_b32 s86, v242, 23
	v_readlane_b32 s87, v242, 24
	v_lshl_add_u64 v[28:29], s[82:83], 0, v[28:29]
	v_readlane_b32 s89, v242, 26
	v_readlane_b32 s90, v242, 27
	v_readlane_b32 s91, v242, 28
	v_readlane_b32 s92, v242, 29
	v_readlane_b32 s93, v242, 30
	v_readlane_b32 s95, v242, 32
	v_lshl_add_u64 v[34:35], s[78:79], 0, v[34:35]
	v_add_u32_e32 v92, 0xffb44000, v36
	v_lshl_add_u32 v93, s2, 2, v1
	v_lshlrev_b32_e32 v36, 2, v0
	v_lshlrev_b32_e32 v38, 1, v0
	v_mov_b32_e32 v96, 0x358637bd
	v_lshlrev_b32_e32 v42, 2, v42
	v_lshlrev_b32_e32 v44, 2, v44
	v_lshlrev_b32_e32 v46, 2, v46
	v_lshlrev_b32_e32 v48, 2, v48
	v_lshlrev_b32_e32 v50, 2, v50
	v_lshlrev_b32_e32 v52, 2, v52
	v_lshlrev_b32_e32 v54, 2, v54
	v_lshlrev_b32_e32 v56, 2, v56
	v_lshlrev_b32_e32 v58, 2, v58
	v_lshlrev_b32_e32 v60, 2, v60
	v_lshlrev_b32_e32 v62, 2, v62
	v_lshlrev_b32_e32 v64, 2, v64
	v_lshlrev_b32_e32 v66, 2, v66
	v_lshlrev_b32_e32 v68, 2, v68
	v_lshlrev_b32_e32 v70, 2, v70
	v_lshlrev_b32_e32 v72, 2, v72
	v_add_u32_e32 v98, 64, v2
	v_xor_b32_e32 v99, 32, v97
	v_xor_b32_e32 v100, 16, v97
	v_xor_b32_e32 v101, 8, v97
	v_xor_b32_e32 v102, 4, v97
	v_xor_b32_e32 v103, 2, v97
	v_xor_b32_e32 v104, 1, v97
	s_lshl_b32 s3, s94, 10
	s_lshl_b32 s10, s94, 2
	s_mov_b32 s11, s2
	s_mov_b32 s7, 0
	v_readlane_b32 s6, v243, 51
	v_readlane_b32 s38, v243, 19
	v_readlane_b32 s39, v243, 20
	v_readlane_b32 s40, v243, 21
	v_readlane_b32 s41, v243, 22
	v_readlane_b32 s44, v243, 25
	v_readlane_b32 s45, v243, 26
	v_readlane_b32 s50, v243, 2
	v_readlane_b32 s51, v243, 3
	v_readlane_b32 s52, v243, 4
	v_readlane_b32 s53, v243, 5
	v_readlane_b32 s54, v243, 6
	v_readlane_b32 s55, v243, 7
	v_readlane_b32 s56, v243, 8
	v_readlane_b32 s57, v243, 9
	v_readlane_b32 s58, v243, 10
	v_readlane_b32 s59, v243, 11
	v_readlane_b32 s60, v243, 12
	v_readlane_b32 s61, v243, 13
	v_readlane_b32 s62, v243, 14
	v_readlane_b32 s63, v243, 15
	v_readlane_b32 s9, v243, 34
	v_readlane_b32 s12, v243, 37
	v_readlane_b32 s13, v243, 38
	v_readlane_b32 s14, v243, 39
	v_readlane_b32 s15, v243, 40
	v_readlane_b32 s16, v243, 41
	v_readlane_b32 s17, v243, 42
	v_readlane_b32 s18, v243, 43
	v_readlane_b32 s19, v243, 44
	v_readlane_b32 s22, v243, 47
	v_readlane_b32 s23, v243, 48
	s_cmpk_lg_i32 s94, 0x200
	s_cbranch_scc1 .Lp0_skip
	global_load_dwordx4 v[140:143], v[34:35], off
	global_load_dwordx4 v[144:147], v[34:35], off offset:1024
	global_load_dwordx4 v[148:151], v[34:35], off offset:2048
	global_load_dwordx4 v[152:155], v[34:35], off offset:3072
	v_readfirstlane_b32 s98, v93
	v_lshrrev_b32_e32 v156, 1, v40
	s_lshl_b32 s99, s98, 12
	s_add_u32 s34, s64, s99
	s_addc_u32 s35, s65, 0
	s_mul_i32 s99, s98, 0x880
	v_readlane_b32 s100, v242, 19
	v_readlane_b32 s101, v242, 20
	s_nop 1
	s_add_u32 s100, s100, s99
	s_addc_u32 s101, s101, 0
	global_load_dwordx4 v[160:163], v40, s[34:35]
	global_load_dwordx4 v[164:167], v40, s[34:35] offset:1024
	global_load_dwordx4 v[168:171], v40, s[34:35] offset:2048
	global_load_dwordx4 v[172:175], v40, s[34:35] offset:3072
	s_add_u32 s34, s34, 0x800000
	s_addc_u32 s35, s35, 0
	global_load_dwordx4 v[176:179], v40, s[34:35]
	global_load_dwordx4 v[180:183], v40, s[34:35] offset:1024
	global_load_dwordx4 v[184:187], v40, s[34:35] offset:2048
	global_load_dwordx4 v[188:191], v40, s[34:35] offset:3072
	s_waitcnt vmcnt(4)
	v_pk_mul_f32 v[192:193], v[160:161], v[160:161]
	v_pk_fma_f32 v[192:193], v[162:163], v[162:163], v[192:193]
	v_pk_fma_f32 v[192:193], v[164:165], v[164:165], v[192:193]
	v_pk_fma_f32 v[192:193], v[166:167], v[166:167], v[192:193]
	v_pk_fma_f32 v[192:193], v[168:169], v[168:169], v[192:193]
	v_pk_fma_f32 v[192:193], v[170:171], v[170:171], v[192:193]
	v_pk_fma_f32 v[192:193], v[172:173], v[172:173], v[192:193]
	v_pk_fma_f32 v[192:193], v[174:175], v[174:175], v[192:193]
	v_add_f32_e32 v192, v192, v193
	s_nop 1
	v_add_f32_dpp v193, v192, v192 quad_perm:[1,0,3,2] row_mask:0xf bank_mask:0xf
	s_nop 1
	v_add_f32_dpp v192, v193, v193 quad_perm:[2,3,0,1] row_mask:0xf bank_mask:0xf
	s_nop 1
	v_add_f32_dpp v193, v192, v192 row_half_mirror row_mask:0xf bank_mask:0xf
	s_nop 1
	v_add_f32_dpp v192, v193, v193 row_mirror row_mask:0xf bank_mask:0xf
	s_nop 1
	v_readlane_b32 s99, v192, 0
	v_readlane_b32 s32, v192, 16
	v_readlane_b32 vcc_lo, v192, 32
	v_readlane_b32 vcc_hi, v192, 48
	s_nop 1
	v_mov_b32_e32 v194, s99
	v_add_f32_e32 v194, s32, v194
	v_add_f32_e32 v194, vcc_lo, v194
	v_add_f32_e32 v194, vcc_hi, v194
	v_fmamk_f32 v194, v194, 0x3a800000, v96
	v_cmp_gt_f32_e32 vcc, 0x800000, v194
	v_mul_f32_e32 v195, 0x4b800000, v194
	s_nop 1
	v_cndmask_b32_e32 v194, v194, v195, vcc
	v_rsq_f32_e32 v194, v194
	s_nop 0
	v_mul_f32_e32 v195, 0x45800000, v194
	v_cndmask_b32_e32 v194, v194, v195, vcc
	v_pk_mul_f32 v[196:197], v[160:161], v[194:195] op_sel_hi:[1,0]
	v_pk_mul_f32 v[198:199], v[162:163], v[194:195] op_sel_hi:[1,0]
	v_pk_mul_f32 v[196:197], v[140:141], v[196:197]
	v_pk_mul_f32 v[198:199], v[142:143], v[198:199]
	v_cvt_pk_bf16_f32 v160, v196, v197
	v_cvt_pk_bf16_f32 v161, v198, v199
	global_store_dwordx2 v156, v[160:161], s[100:101]
	v_pk_mul_f32 v[196:197], v[164:165], v[194:195] op_sel_hi:[1,0]
	v_pk_mul_f32 v[198:199], v[166:167], v[194:195] op_sel_hi:[1,0]
	v_pk_mul_f32 v[196:197], v[144:145], v[196:197]
	v_pk_mul_f32 v[198:199], v[146:147], v[198:199]
	v_cvt_pk_bf16_f32 v164, v196, v197
	v_cvt_pk_bf16_f32 v165, v198, v199
	global_store_dwordx2 v156, v[164:165], s[100:101] offset:512
	v_pk_mul_f32 v[196:197], v[168:169], v[194:195] op_sel_hi:[1,0]
	v_pk_mul_f32 v[198:199], v[170:171], v[194:195] op_sel_hi:[1,0]
	v_pk_mul_f32 v[196:197], v[148:149], v[196:197]
	v_pk_mul_f32 v[198:199], v[150:151], v[198:199]
	v_cvt_pk_bf16_f32 v168, v196, v197
	v_cvt_pk_bf16_f32 v169, v198, v199
	global_store_dwordx2 v156, v[168:169], s[100:101] offset:1024
	v_pk_mul_f32 v[196:197], v[172:173], v[194:195] op_sel_hi:[1,0]
	v_pk_mul_f32 v[198:199], v[174:175], v[194:195] op_sel_hi:[1,0]
	v_pk_mul_f32 v[196:197], v[152:153], v[196:197]
	v_pk_mul_f32 v[198:199], v[154:155], v[198:199]
	v_cvt_pk_bf16_f32 v172, v196, v197
	v_cvt_pk_bf16_f32 v173, v198, v199
	global_store_dwordx2 v156, v[172:173], s[100:101] offset:1536
	s_add_u32 s100, s100, 0x440000
	s_addc_u32 s101, s101, 0
	s_add_u32 s34, s34, 0x800000
	s_addc_u32 s35, s35, 0
	global_load_dwordx4 v[160:163], v40, s[34:35]
	global_load_dwordx4 v[164:167], v40, s[34:35] offset:1024
	global_load_dwordx4 v[168:171], v40, s[34:35] offset:2048
	global_load_dwordx4 v[172:175], v40, s[34:35] offset:3072
	s_waitcnt vmcnt(8)
	v_pk_mul_f32 v[192:193], v[176:177], v[176:177]
	v_pk_fma_f32 v[192:193], v[178:179], v[178:179], v[192:193]
	v_pk_fma_f32 v[192:193], v[180:181], v[180:181], v[192:193]
	v_pk_fma_f32 v[192:193], v[182:183], v[182:183], v[192:193]
	v_pk_fma_f32 v[192:193], v[184:185], v[184:185], v[192:193]
	v_pk_fma_f32 v[192:193], v[186:187], v[186:187], v[192:193]
	v_pk_fma_f32 v[192:193], v[188:189], v[188:189], v[192:193]
	v_pk_fma_f32 v[192:193], v[190:191], v[190:191], v[192:193]
	v_add_f32_e32 v192, v192, v193
	s_nop 1
	v_add_f32_dpp v193, v192, v192 quad_perm:[1,0,3,2] row_mask:0xf bank_mask:0xf
	s_nop 1
	v_add_f32_dpp v192, v193, v193 quad_perm:[2,3,0,1] row_mask:0xf bank_mask:0xf
	s_nop 1
	v_add_f32_dpp v193, v192, v192 row_half_mirror row_mask:0xf bank_mask:0xf
	s_nop 1
	v_add_f32_dpp v192, v193, v193 row_mirror row_mask:0xf bank_mask:0xf
	s_nop 1
	v_readlane_b32 s99, v192, 0
	v_readlane_b32 s32, v192, 16
	v_readlane_b32 vcc_lo, v192, 32
	v_readlane_b32 vcc_hi, v192, 48
	s_nop 1
	v_mov_b32_e32 v194, s99
	v_add_f32_e32 v194, s32, v194
	v_add_f32_e32 v194, vcc_lo, v194
	v_add_f32_e32 v194, vcc_hi, v194
	v_fmamk_f32 v194, v194, 0x3a800000, v96
	v_cmp_gt_f32_e32 vcc, 0x800000, v194
	v_mul_f32_e32 v195, 0x4b800000, v194
	s_nop 1
	v_cndmask_b32_e32 v194, v194, v195, vcc
	v_rsq_f32_e32 v194, v194
	s_nop 0
	v_mul_f32_e32 v195, 0x45800000, v194
	v_cndmask_b32_e32 v194, v194, v195, vcc
	v_pk_mul_f32 v[196:197], v[176:177], v[194:195] op_sel_hi:[1,0]
	v_pk_mul_f32 v[198:199], v[178:179], v[194:195] op_sel_hi:[1,0]
	v_pk_mul_f32 v[196:197], v[140:141], v[196:197]
	v_pk_mul_f32 v[198:199], v[142:143], v[198:199]
	v_cvt_pk_bf16_f32 v176, v196, v197
	v_cvt_pk_bf16_f32 v177, v198, v199
	global_store_dwordx2 v156, v[176:177], s[100:101]
	v_pk_mul_f32 v[196:197], v[180:181], v[194:195] op_sel_hi:[1,0]
	v_pk_mul_f32 v[198:199], v[182:183], v[194:195] op_sel_hi:[1,0]
	v_pk_mul_f32 v[196:197], v[144:145], v[196:197]
	v_pk_mul_f32 v[198:199], v[146:147], v[198:199]
	v_cvt_pk_bf16_f32 v180, v196, v197
	v_cvt_pk_bf16_f32 v181, v198, v199
	global_store_dwordx2 v156, v[180:181], s[100:101] offset:512
	v_pk_mul_f32 v[196:197], v[184:185], v[194:195] op_sel_hi:[1,0]
	v_pk_mul_f32 v[198:199], v[186:187], v[194:195] op_sel_hi:[1,0]
	v_pk_mul_f32 v[196:197], v[148:149], v[196:197]
	v_pk_mul_f32 v[198:199], v[150:151], v[198:199]
	v_cvt_pk_bf16_f32 v184, v196, v197
	v_cvt_pk_bf16_f32 v185, v198, v199
	global_store_dwordx2 v156, v[184:185], s[100:101] offset:1024
	v_pk_mul_f32 v[196:197], v[188:189], v[194:195] op_sel_hi:[1,0]
	v_pk_mul_f32 v[198:199], v[190:191], v[194:195] op_sel_hi:[1,0]
	v_pk_mul_f32 v[196:197], v[152:153], v[196:197]
	v_pk_mul_f32 v[198:199], v[154:155], v[198:199]
	v_cvt_pk_bf16_f32 v188, v196, v197
	v_cvt_pk_bf16_f32 v189, v198, v199
	global_store_dwordx2 v156, v[188:189], s[100:101] offset:1536
	s_add_u32 s100, s100, 0x440000
	s_addc_u32 s101, s101, 0
	s_add_u32 s34, s34, 0x800000
	s_addc_u32 s35, s35, 0
	global_load_dwordx4 v[176:179], v40, s[34:35]
	global_load_dwordx4 v[180:183], v40, s[34:35] offset:1024
	global_load_dwordx4 v[184:187], v40, s[34:35] offset:2048
	global_load_dwordx4 v[188:191], v40, s[34:35] offset:3072
	s_waitcnt vmcnt(8)
	v_pk_mul_f32 v[192:193], v[160:161], v[160:161]
	v_pk_fma_f32 v[192:193], v[162:163], v[162:163], v[192:193]
	v_pk_fma_f32 v[192:193], v[164:165], v[164:165], v[192:193]
	v_pk_fma_f32 v[192:193], v[166:167], v[166:167], v[192:193]
	v_pk_fma_f32 v[192:193], v[168:169], v[168:169], v[192:193]
	v_pk_fma_f32 v[192:193], v[170:171], v[170:171], v[192:193]
	v_pk_fma_f32 v[192:193], v[172:173], v[172:173], v[192:193]
	v_pk_fma_f32 v[192:193], v[174:175], v[174:175], v[192:193]
	v_add_f32_e32 v192, v192, v193
	s_nop 1
	v_add_f32_dpp v193, v192, v192 quad_perm:[1,0,3,2] row_mask:0xf bank_mask:0xf
	s_nop 1
	v_add_f32_dpp v192, v193, v193 quad_perm:[2,3,0,1] row_mask:0xf bank_mask:0xf
	s_nop 1
	v_add_f32_dpp v193, v192, v192 row_half_mirror row_mask:0xf bank_mask:0xf
	s_nop 1
	v_add_f32_dpp v192, v193, v193 row_mirror row_mask:0xf bank_mask:0xf
	s_nop 1
	v_readlane_b32 s99, v192, 0
	v_readlane_b32 s32, v192, 16
	v_readlane_b32 vcc_lo, v192, 32
	v_readlane_b32 vcc_hi, v192, 48
	s_nop 1
	v_mov_b32_e32 v194, s99
	v_add_f32_e32 v194, s32, v194
	v_add_f32_e32 v194, vcc_lo, v194
	v_add_f32_e32 v194, vcc_hi, v194
	v_fmamk_f32 v194, v194, 0x3a800000, v96
	v_cmp_gt_f32_e32 vcc, 0x800000, v194
	v_mul_f32_e32 v195, 0x4b800000, v194
	s_nop 1
	v_cndmask_b32_e32 v194, v194, v195, vcc
	v_rsq_f32_e32 v194, v194
	s_nop 0
	v_mul_f32_e32 v195, 0x45800000, v194
	v_cndmask_b32_e32 v194, v194, v195, vcc
	v_pk_mul_f32 v[196:197], v[160:161], v[194:195] op_sel_hi:[1,0]
	v_pk_mul_f32 v[198:199], v[162:163], v[194:195] op_sel_hi:[1,0]
	v_pk_mul_f32 v[196:197], v[140:141], v[196:197]
	v_pk_mul_f32 v[198:199], v[142:143], v[198:199]
	v_cvt_pk_bf16_f32 v160, v196, v197
	v_cvt_pk_bf16_f32 v161, v198, v199
	global_store_dwordx2 v156, v[160:161], s[100:101]
	v_pk_mul_f32 v[196:197], v[164:165], v[194:195] op_sel_hi:[1,0]
	v_pk_mul_f32 v[198:199], v[166:167], v[194:195] op_sel_hi:[1,0]
	v_pk_mul_f32 v[196:197], v[144:145], v[196:197]
	v_pk_mul_f32 v[198:199], v[146:147], v[198:199]
	v_cvt_pk_bf16_f32 v164, v196, v197
	v_cvt_pk_bf16_f32 v165, v198, v199
	global_store_dwordx2 v156, v[164:165], s[100:101] offset:512
	v_pk_mul_f32 v[196:197], v[168:169], v[194:195] op_sel_hi:[1,0]
	v_pk_mul_f32 v[198:199], v[170:171], v[194:195] op_sel_hi:[1,0]
	v_pk_mul_f32 v[196:197], v[148:149], v[196:197]
	v_pk_mul_f32 v[198:199], v[150:151], v[198:199]
	v_cvt_pk_bf16_f32 v168, v196, v197
	v_cvt_pk_bf16_f32 v169, v198, v199
	global_store_dwordx2 v156, v[168:169], s[100:101] offset:1024
	v_pk_mul_f32 v[196:197], v[172:173], v[194:195] op_sel_hi:[1,0]
	v_pk_mul_f32 v[198:199], v[174:175], v[194:195] op_sel_hi:[1,0]
	v_pk_mul_f32 v[196:197], v[152:153], v[196:197]
	v_pk_mul_f32 v[198:199], v[154:155], v[198:199]
	v_cvt_pk_bf16_f32 v172, v196, v197
	v_cvt_pk_bf16_f32 v173, v198, v199
	global_store_dwordx2 v156, v[172:173], s[100:101] offset:1536
	s_add_u32 s100, s100, 0x440000
	s_addc_u32 s101, s101, 0
	s_add_u32 s34, s34, 0x800000
	s_addc_u32 s35, s35, 0
	global_load_dwordx4 v[160:163], v40, s[34:35]
	global_load_dwordx4 v[164:167], v40, s[34:35] offset:1024
	global_load_dwordx4 v[168:171], v40, s[34:35] offset:2048
	global_load_dwordx4 v[172:175], v40, s[34:35] offset:3072
	s_waitcnt vmcnt(8)
	v_pk_mul_f32 v[192:193], v[176:177], v[176:177]
	v_pk_fma_f32 v[192:193], v[178:179], v[178:179], v[192:193]
	v_pk_fma_f32 v[192:193], v[180:181], v[180:181], v[192:193]
	v_pk_fma_f32 v[192:193], v[182:183], v[182:183], v[192:193]
	v_pk_fma_f32 v[192:193], v[184:185], v[184:185], v[192:193]
	v_pk_fma_f32 v[192:193], v[186:187], v[186:187], v[192:193]
	v_pk_fma_f32 v[192:193], v[188:189], v[188:189], v[192:193]
	v_pk_fma_f32 v[192:193], v[190:191], v[190:191], v[192:193]
	v_add_f32_e32 v192, v192, v193
	s_nop 1
	v_add_f32_dpp v193, v192, v192 quad_perm:[1,0,3,2] row_mask:0xf bank_mask:0xf
	s_nop 1
	v_add_f32_dpp v192, v193, v193 quad_perm:[2,3,0,1] row_mask:0xf bank_mask:0xf
	s_nop 1
	v_add_f32_dpp v193, v192, v192 row_half_mirror row_mask:0xf bank_mask:0xf
	s_nop 1
	v_add_f32_dpp v192, v193, v193 row_mirror row_mask:0xf bank_mask:0xf
	s_nop 1
	v_readlane_b32 s99, v192, 0
	v_readlane_b32 s32, v192, 16
	v_readlane_b32 vcc_lo, v192, 32
	v_readlane_b32 vcc_hi, v192, 48
	s_nop 1
	v_mov_b32_e32 v194, s99
	v_add_f32_e32 v194, s32, v194
	v_add_f32_e32 v194, vcc_lo, v194
	v_add_f32_e32 v194, vcc_hi, v194
	v_fmamk_f32 v194, v194, 0x3a800000, v96
	v_cmp_gt_f32_e32 vcc, 0x800000, v194
	v_mul_f32_e32 v195, 0x4b800000, v194
	s_nop 1
	v_cndmask_b32_e32 v194, v194, v195, vcc
	v_rsq_f32_e32 v194, v194
	s_nop 0
	v_mul_f32_e32 v195, 0x45800000, v194
	v_cndmask_b32_e32 v194, v194, v195, vcc
	v_pk_mul_f32 v[196:197], v[176:177], v[194:195] op_sel_hi:[1,0]
	v_pk_mul_f32 v[198:199], v[178:179], v[194:195] op_sel_hi:[1,0]
	v_pk_mul_f32 v[196:197], v[140:141], v[196:197]
	v_pk_mul_f32 v[198:199], v[142:143], v[198:199]
	v_cvt_pk_bf16_f32 v176, v196, v197
	v_cvt_pk_bf16_f32 v177, v198, v199
	global_store_dwordx2 v156, v[176:177], s[100:101]
	v_pk_mul_f32 v[196:197], v[180:181], v[194:195] op_sel_hi:[1,0]
	v_pk_mul_f32 v[198:199], v[182:183], v[194:195] op_sel_hi:[1,0]
	v_pk_mul_f32 v[196:197], v[144:145], v[196:197]
	v_pk_mul_f32 v[198:199], v[146:147], v[198:199]
	v_cvt_pk_bf16_f32 v180, v196, v197
	v_cvt_pk_bf16_f32 v181, v198, v199
	global_store_dwordx2 v156, v[180:181], s[100:101] offset:512
	v_pk_mul_f32 v[196:197], v[184:185], v[194:195] op_sel_hi:[1,0]
	v_pk_mul_f32 v[198:199], v[186:187], v[194:195] op_sel_hi:[1,0]
	v_pk_mul_f32 v[196:197], v[148:149], v[196:197]
	v_pk_mul_f32 v[198:199], v[150:151], v[198:199]
	v_cvt_pk_bf16_f32 v184, v196, v197
	v_cvt_pk_bf16_f32 v185, v198, v199
	global_store_dwordx2 v156, v[184:185], s[100:101] offset:1024
	v_pk_mul_f32 v[196:197], v[188:189], v[194:195] op_sel_hi:[1,0]
	v_pk_mul_f32 v[198:199], v[190:191], v[194:195] op_sel_hi:[1,0]
	v_pk_mul_f32 v[196:197], v[152:153], v[196:197]
	v_pk_mul_f32 v[198:199], v[154:155], v[198:199]
	v_cvt_pk_bf16_f32 v188, v196, v197
	v_cvt_pk_bf16_f32 v189, v198, v199
	global_store_dwordx2 v156, v[188:189], s[100:101] offset:1536
	s_add_u32 s100, s100, 0x440000
	s_addc_u32 s101, s101, 0
	s_add_u32 s34, s34, 0x800000
	s_addc_u32 s35, s35, 0
	global_load_dwordx4 v[176:179], v40, s[34:35]
	global_load_dwordx4 v[180:183], v40, s[34:35] offset:1024
	global_load_dwordx4 v[184:187], v40, s[34:35] offset:2048
	global_load_dwordx4 v[188:191], v40, s[34:35] offset:3072
	s_waitcnt vmcnt(8)
	v_pk_mul_f32 v[192:193], v[160:161], v[160:161]
	v_pk_fma_f32 v[192:193], v[162:163], v[162:163], v[192:193]
	v_pk_fma_f32 v[192:193], v[164:165], v[164:165], v[192:193]
	v_pk_fma_f32 v[192:193], v[166:167], v[166:167], v[192:193]
	v_pk_fma_f32 v[192:193], v[168:169], v[168:169], v[192:193]
	v_pk_fma_f32 v[192:193], v[170:171], v[170:171], v[192:193]
	v_pk_fma_f32 v[192:193], v[172:173], v[172:173], v[192:193]
	v_pk_fma_f32 v[192:193], v[174:175], v[174:175], v[192:193]
	v_add_f32_e32 v192, v192, v193
	s_nop 1
	v_add_f32_dpp v193, v192, v192 quad_perm:[1,0,3,2] row_mask:0xf bank_mask:0xf
	s_nop 1
	v_add_f32_dpp v192, v193, v193 quad_perm:[2,3,0,1] row_mask:0xf bank_mask:0xf
	s_nop 1
	v_add_f32_dpp v193, v192, v192 row_half_mirror row_mask:0xf bank_mask:0xf
	s_nop 1
	v_add_f32_dpp v192, v193, v193 row_mirror row_mask:0xf bank_mask:0xf
	s_nop 1
	v_readlane_b32 s99, v192, 0
	v_readlane_b32 s32, v192, 16
	v_readlane_b32 vcc_lo, v192, 32
	v_readlane_b32 vcc_hi, v192, 48
	s_nop 1
	v_mov_b32_e32 v194, s99
	v_add_f32_e32 v194, s32, v194
	v_add_f32_e32 v194, vcc_lo, v194
	v_add_f32_e32 v194, vcc_hi, v194
	v_fmamk_f32 v194, v194, 0x3a800000, v96
	v_cmp_gt_f32_e32 vcc, 0x800000, v194
	v_mul_f32_e32 v195, 0x4b800000, v194
	s_nop 1
	v_cndmask_b32_e32 v194, v194, v195, vcc
	v_rsq_f32_e32 v194, v194
	s_nop 0
	v_mul_f32_e32 v195, 0x45800000, v194
	v_cndmask_b32_e32 v194, v194, v195, vcc
	v_pk_mul_f32 v[196:197], v[160:161], v[194:195] op_sel_hi:[1,0]
	v_pk_mul_f32 v[198:199], v[162:163], v[194:195] op_sel_hi:[1,0]
	v_pk_mul_f32 v[196:197], v[140:141], v[196:197]
	v_pk_mul_f32 v[198:199], v[142:143], v[198:199]
	v_cvt_pk_bf16_f32 v160, v196, v197
	v_cvt_pk_bf16_f32 v161, v198, v199
	global_store_dwordx2 v156, v[160:161], s[100:101]
	v_pk_mul_f32 v[196:197], v[164:165], v[194:195] op_sel_hi:[1,0]
	v_pk_mul_f32 v[198:199], v[166:167], v[194:195] op_sel_hi:[1,0]
	v_pk_mul_f32 v[196:197], v[144:145], v[196:197]
	v_pk_mul_f32 v[198:199], v[146:147], v[198:199]
	v_cvt_pk_bf16_f32 v164, v196, v197
	v_cvt_pk_bf16_f32 v165, v198, v199
	global_store_dwordx2 v156, v[164:165], s[100:101] offset:512
	v_pk_mul_f32 v[196:197], v[168:169], v[194:195] op_sel_hi:[1,0]
	v_pk_mul_f32 v[198:199], v[170:171], v[194:195] op_sel_hi:[1,0]
	v_pk_mul_f32 v[196:197], v[148:149], v[196:197]
	v_pk_mul_f32 v[198:199], v[150:151], v[198:199]
	v_cvt_pk_bf16_f32 v168, v196, v197
	v_cvt_pk_bf16_f32 v169, v198, v199
	global_store_dwordx2 v156, v[168:169], s[100:101] offset:1024
	v_pk_mul_f32 v[196:197], v[172:173], v[194:195] op_sel_hi:[1,0]
	v_pk_mul_f32 v[198:199], v[174:175], v[194:195] op_sel_hi:[1,0]
	v_pk_mul_f32 v[196:197], v[152:153], v[196:197]
	v_pk_mul_f32 v[198:199], v[154:155], v[198:199]
	v_cvt_pk_bf16_f32 v172, v196, v197
	v_cvt_pk_bf16_f32 v173, v198, v199
	global_store_dwordx2 v156, v[172:173], s[100:101] offset:1536
	s_add_u32 s100, s100, 0x440000
	s_addc_u32 s101, s101, 0
	s_add_u32 s34, s34, 0x800000
	s_addc_u32 s35, s35, 0
	global_load_dwordx4 v[160:163], v40, s[34:35]
	global_load_dwordx4 v[164:167], v40, s[34:35] offset:1024
	global_load_dwordx4 v[168:171], v40, s[34:35] offset:2048
	global_load_dwordx4 v[172:175], v40, s[34:35] offset:3072
	s_waitcnt vmcnt(8)
	v_pk_mul_f32 v[192:193], v[176:177], v[176:177]
	v_pk_fma_f32 v[192:193], v[178:179], v[178:179], v[192:193]
	v_pk_fma_f32 v[192:193], v[180:181], v[180:181], v[192:193]
	v_pk_fma_f32 v[192:193], v[182:183], v[182:183], v[192:193]
	v_pk_fma_f32 v[192:193], v[184:185], v[184:185], v[192:193]
	v_pk_fma_f32 v[192:193], v[186:187], v[186:187], v[192:193]
	v_pk_fma_f32 v[192:193], v[188:189], v[188:189], v[192:193]
	v_pk_fma_f32 v[192:193], v[190:191], v[190:191], v[192:193]
	v_add_f32_e32 v192, v192, v193
	s_nop 1
	v_add_f32_dpp v193, v192, v192 quad_perm:[1,0,3,2] row_mask:0xf bank_mask:0xf
	s_nop 1
	v_add_f32_dpp v192, v193, v193 quad_perm:[2,3,0,1] row_mask:0xf bank_mask:0xf
	s_nop 1
	v_add_f32_dpp v193, v192, v192 row_half_mirror row_mask:0xf bank_mask:0xf
	s_nop 1
	v_add_f32_dpp v192, v193, v193 row_mirror row_mask:0xf bank_mask:0xf
	s_nop 1
	v_readlane_b32 s99, v192, 0
	v_readlane_b32 s32, v192, 16
	v_readlane_b32 vcc_lo, v192, 32
	v_readlane_b32 vcc_hi, v192, 48
	s_nop 1
	v_mov_b32_e32 v194, s99
	v_add_f32_e32 v194, s32, v194
	v_add_f32_e32 v194, vcc_lo, v194
	v_add_f32_e32 v194, vcc_hi, v194
	v_fmamk_f32 v194, v194, 0x3a800000, v96
	v_cmp_gt_f32_e32 vcc, 0x800000, v194
	v_mul_f32_e32 v195, 0x4b800000, v194
	s_nop 1
	v_cndmask_b32_e32 v194, v194, v195, vcc
	v_rsq_f32_e32 v194, v194
	s_nop 0
	v_mul_f32_e32 v195, 0x45800000, v194
	v_cndmask_b32_e32 v194, v194, v195, vcc
	v_pk_mul_f32 v[196:197], v[176:177], v[194:195] op_sel_hi:[1,0]
	v_pk_mul_f32 v[198:199], v[178:179], v[194:195] op_sel_hi:[1,0]
	v_pk_mul_f32 v[196:197], v[140:141], v[196:197]
	v_pk_mul_f32 v[198:199], v[142:143], v[198:199]
	v_cvt_pk_bf16_f32 v176, v196, v197
	v_cvt_pk_bf16_f32 v177, v198, v199
	global_store_dwordx2 v156, v[176:177], s[100:101]
	v_pk_mul_f32 v[196:197], v[180:181], v[194:195] op_sel_hi:[1,0]
	v_pk_mul_f32 v[198:199], v[182:183], v[194:195] op_sel_hi:[1,0]
	v_pk_mul_f32 v[196:197], v[144:145], v[196:197]
	v_pk_mul_f32 v[198:199], v[146:147], v[198:199]
	v_cvt_pk_bf16_f32 v180, v196, v197
	v_cvt_pk_bf16_f32 v181, v198, v199
	global_store_dwordx2 v156, v[180:181], s[100:101] offset:512
	v_pk_mul_f32 v[196:197], v[184:185], v[194:195] op_sel_hi:[1,0]
	v_pk_mul_f32 v[198:199], v[186:187], v[194:195] op_sel_hi:[1,0]
	v_pk_mul_f32 v[196:197], v[148:149], v[196:197]
	v_pk_mul_f32 v[198:199], v[150:151], v[198:199]
	v_cvt_pk_bf16_f32 v184, v196, v197
	v_cvt_pk_bf16_f32 v185, v198, v199
	global_store_dwordx2 v156, v[184:185], s[100:101] offset:1024
	v_pk_mul_f32 v[196:197], v[188:189], v[194:195] op_sel_hi:[1,0]
	v_pk_mul_f32 v[198:199], v[190:191], v[194:195] op_sel_hi:[1,0]
	v_pk_mul_f32 v[196:197], v[152:153], v[196:197]
	v_pk_mul_f32 v[198:199], v[154:155], v[198:199]
	v_cvt_pk_bf16_f32 v188, v196, v197
	v_cvt_pk_bf16_f32 v189, v198, v199
	global_store_dwordx2 v156, v[188:189], s[100:101] offset:1536
	s_add_u32 s100, s100, 0x440000
	s_addc_u32 s101, s101, 0
	s_add_u32 s34, s34, 0x800000
	s_addc_u32 s35, s35, 0
	global_load_dwordx4 v[176:179], v40, s[34:35]
	global_load_dwordx4 v[180:183], v40, s[34:35] offset:1024
	global_load_dwordx4 v[184:187], v40, s[34:35] offset:2048
	global_load_dwordx4 v[188:191], v40, s[34:35] offset:3072
	s_waitcnt vmcnt(8)
	v_pk_mul_f32 v[192:193], v[160:161], v[160:161]
	v_pk_fma_f32 v[192:193], v[162:163], v[162:163], v[192:193]
	v_pk_fma_f32 v[192:193], v[164:165], v[164:165], v[192:193]
	v_pk_fma_f32 v[192:193], v[166:167], v[166:167], v[192:193]
	v_pk_fma_f32 v[192:193], v[168:169], v[168:169], v[192:193]
	v_pk_fma_f32 v[192:193], v[170:171], v[170:171], v[192:193]
	v_pk_fma_f32 v[192:193], v[172:173], v[172:173], v[192:193]
	v_pk_fma_f32 v[192:193], v[174:175], v[174:175], v[192:193]
	v_add_f32_e32 v192, v192, v193
	s_nop 1
	v_add_f32_dpp v193, v192, v192 quad_perm:[1,0,3,2] row_mask:0xf bank_mask:0xf
	s_nop 1
	v_add_f32_dpp v192, v193, v193 quad_perm:[2,3,0,1] row_mask:0xf bank_mask:0xf
	s_nop 1
	v_add_f32_dpp v193, v192, v192 row_half_mirror row_mask:0xf bank_mask:0xf
	s_nop 1
	v_add_f32_dpp v192, v193, v193 row_mirror row_mask:0xf bank_mask:0xf
	s_nop 1
	v_readlane_b32 s99, v192, 0
	v_readlane_b32 s32, v192, 16
	v_readlane_b32 vcc_lo, v192, 32
	v_readlane_b32 vcc_hi, v192, 48
	s_nop 1
	v_mov_b32_e32 v194, s99
	v_add_f32_e32 v194, s32, v194
	v_add_f32_e32 v194, vcc_lo, v194
	v_add_f32_e32 v194, vcc_hi, v194
	v_fmamk_f32 v194, v194, 0x3a800000, v96
	v_cmp_gt_f32_e32 vcc, 0x800000, v194
	v_mul_f32_e32 v195, 0x4b800000, v194
	s_nop 1
	v_cndmask_b32_e32 v194, v194, v195, vcc
	v_rsq_f32_e32 v194, v194
	s_nop 0
	v_mul_f32_e32 v195, 0x45800000, v194
	v_cndmask_b32_e32 v194, v194, v195, vcc
	v_pk_mul_f32 v[196:197], v[160:161], v[194:195] op_sel_hi:[1,0]
	v_pk_mul_f32 v[198:199], v[162:163], v[194:195] op_sel_hi:[1,0]
	v_pk_mul_f32 v[196:197], v[140:141], v[196:197]
	v_pk_mul_f32 v[198:199], v[142:143], v[198:199]
	v_cvt_pk_bf16_f32 v160, v196, v197
	v_cvt_pk_bf16_f32 v161, v198, v199
	global_store_dwordx2 v156, v[160:161], s[100:101]
	v_pk_mul_f32 v[196:197], v[164:165], v[194:195] op_sel_hi:[1,0]
	v_pk_mul_f32 v[198:199], v[166:167], v[194:195] op_sel_hi:[1,0]
	v_pk_mul_f32 v[196:197], v[144:145], v[196:197]
	v_pk_mul_f32 v[198:199], v[146:147], v[198:199]
	v_cvt_pk_bf16_f32 v164, v196, v197
	v_cvt_pk_bf16_f32 v165, v198, v199
	global_store_dwordx2 v156, v[164:165], s[100:101] offset:512
	v_pk_mul_f32 v[196:197], v[168:169], v[194:195] op_sel_hi:[1,0]
	v_pk_mul_f32 v[198:199], v[170:171], v[194:195] op_sel_hi:[1,0]
	v_pk_mul_f32 v[196:197], v[148:149], v[196:197]
	v_pk_mul_f32 v[198:199], v[150:151], v[198:199]
	v_cvt_pk_bf16_f32 v168, v196, v197
	v_cvt_pk_bf16_f32 v169, v198, v199
	global_store_dwordx2 v156, v[168:169], s[100:101] offset:1024
	v_pk_mul_f32 v[196:197], v[172:173], v[194:195] op_sel_hi:[1,0]
	v_pk_mul_f32 v[198:199], v[174:175], v[194:195] op_sel_hi:[1,0]
	v_pk_mul_f32 v[196:197], v[152:153], v[196:197]
	v_pk_mul_f32 v[198:199], v[154:155], v[198:199]
	v_cvt_pk_bf16_f32 v172, v196, v197
	v_cvt_pk_bf16_f32 v173, v198, v199
	global_store_dwordx2 v156, v[172:173], s[100:101] offset:1536
	s_add_u32 s100, s100, 0x440000
	s_addc_u32 s101, s101, 0
	s_waitcnt vmcnt(4)
	v_pk_mul_f32 v[192:193], v[176:177], v[176:177]
	v_pk_fma_f32 v[192:193], v[178:179], v[178:179], v[192:193]
	v_pk_fma_f32 v[192:193], v[180:181], v[180:181], v[192:193]
	v_pk_fma_f32 v[192:193], v[182:183], v[182:183], v[192:193]
	v_pk_fma_f32 v[192:193], v[184:185], v[184:185], v[192:193]
	v_pk_fma_f32 v[192:193], v[186:187], v[186:187], v[192:193]
	v_pk_fma_f32 v[192:193], v[188:189], v[188:189], v[192:193]
	v_pk_fma_f32 v[192:193], v[190:191], v[190:191], v[192:193]
	v_add_f32_e32 v192, v192, v193
	s_nop 1
	v_add_f32_dpp v193, v192, v192 quad_perm:[1,0,3,2] row_mask:0xf bank_mask:0xf
	s_nop 1
	v_add_f32_dpp v192, v193, v193 quad_perm:[2,3,0,1] row_mask:0xf bank_mask:0xf
	s_nop 1
	v_add_f32_dpp v193, v192, v192 row_half_mirror row_mask:0xf bank_mask:0xf
	s_nop 1
	v_add_f32_dpp v192, v193, v193 row_mirror row_mask:0xf bank_mask:0xf
	s_nop 1
	v_readlane_b32 s99, v192, 0
	v_readlane_b32 s32, v192, 16
	v_readlane_b32 vcc_lo, v192, 32
	v_readlane_b32 vcc_hi, v192, 48
	s_nop 1
	v_mov_b32_e32 v194, s99
	v_add_f32_e32 v194, s32, v194
	v_add_f32_e32 v194, vcc_lo, v194
	v_add_f32_e32 v194, vcc_hi, v194
	v_fmamk_f32 v194, v194, 0x3a800000, v96
	v_cmp_gt_f32_e32 vcc, 0x800000, v194
	v_mul_f32_e32 v195, 0x4b800000, v194
	s_nop 1
	v_cndmask_b32_e32 v194, v194, v195, vcc
	v_rsq_f32_e32 v194, v194
	s_nop 0
	v_mul_f32_e32 v195, 0x45800000, v194
	v_cndmask_b32_e32 v194, v194, v195, vcc
	v_pk_mul_f32 v[196:197], v[176:177], v[194:195] op_sel_hi:[1,0]
	v_pk_mul_f32 v[198:199], v[178:179], v[194:195] op_sel_hi:[1,0]
	v_pk_mul_f32 v[196:197], v[140:141], v[196:197]
	v_pk_mul_f32 v[198:199], v[142:143], v[198:199]
	v_cvt_pk_bf16_f32 v176, v196, v197
	v_cvt_pk_bf16_f32 v177, v198, v199
	global_store_dwordx2 v156, v[176:177], s[100:101]
	v_pk_mul_f32 v[196:197], v[180:181], v[194:195] op_sel_hi:[1,0]
	v_pk_mul_f32 v[198:199], v[182:183], v[194:195] op_sel_hi:[1,0]
	v_pk_mul_f32 v[196:197], v[144:145], v[196:197]
	v_pk_mul_f32 v[198:199], v[146:147], v[198:199]
	v_cvt_pk_bf16_f32 v180, v196, v197
	v_cvt_pk_bf16_f32 v181, v198, v199
	global_store_dwordx2 v156, v[180:181], s[100:101] offset:512
	v_pk_mul_f32 v[196:197], v[184:185], v[194:195] op_sel_hi:[1,0]
	v_pk_mul_f32 v[198:199], v[186:187], v[194:195] op_sel_hi:[1,0]
	v_pk_mul_f32 v[196:197], v[148:149], v[196:197]
	v_pk_mul_f32 v[198:199], v[150:151], v[198:199]
	v_cvt_pk_bf16_f32 v184, v196, v197
	v_cvt_pk_bf16_f32 v185, v198, v199
	global_store_dwordx2 v156, v[184:185], s[100:101] offset:1024
	v_pk_mul_f32 v[196:197], v[188:189], v[194:195] op_sel_hi:[1,0]
	v_pk_mul_f32 v[198:199], v[190:191], v[194:195] op_sel_hi:[1,0]
	v_pk_mul_f32 v[196:197], v[152:153], v[196:197]
	v_pk_mul_f32 v[198:199], v[154:155], v[198:199]
	v_cvt_pk_bf16_f32 v188, v196, v197
	v_cvt_pk_bf16_f32 v189, v198, v199
	global_store_dwordx2 v156, v[188:189], s[100:101] offset:1536
	s_add_u32 s100, s100, 0x440000
	s_addc_u32 s101, s101, 0
	s_lshl_b32 s99, s94, 3
	s_add_i32 s11, s11, s99
	s_lshl_b32 s99, s10, 3
	v_add_u32_e32 v93, s99, v93
	s_lshl_b32 s99, s3, 3
	v_add_u32_e32 v92, s99, v92

.LBB0_1604:
	s_waitcnt lgkmcnt(0)
	v_lshrrev_b32_e32 v13, 5, v6
	v_add_u32_e32 v4, s10, v13
	v_mov_b32_e32 v5, 0
	v_lshl_add_u64 v[54:55], v[4:5], 2, s[42:43]
	v_lshl_add_u64 v[56:57], v[4:5], 2, s[14:15]
	v_lshlrev_b64 v[52:53], 11, v[4:5]
	v_lshl_add_u64 v[52:53], v[2:3], 0, v[52:53]
	v_lshlrev_b64 v[48:49], 12, v[4:5]
	v_lshl_add_u64 v[48:49], v[0:1], 0, v[48:49]
	v_mov_b32_e32 v50, v48
	v_mov_b32_e32 v51, v49
	s_mov_b32 s98, 0x4000
	s_mov_b32 s99, 0
	s_mov_b32 s100, 0x8000
	s_mov_b32 s101, 0
	v_lshlrev_b32_e32 v19, 2, v13
	v_lshlrev_b32_e32 v18, 9, v13
	v_bitop3_b32 v19, v19, v7, 16 bitop3:0x6c
	v_lshl_or_b32 v58, v19, 2, v18
	global_load_dword v112, v[54:55], off offset:0
	global_load_dwordx2 v[96:97], v[52:53], off
	v_lshl_add_u64 v[52:53], v[52:53], 0, s[98:99]
	global_load_dwordx4 v[64:67], v[48:49], off
	v_lshl_add_u64 v[48:49], v[48:49], 0, s[100:101]
	global_load_dword v113, v[54:55], off offset:32
	global_load_dwordx2 v[98:99], v[52:53], off
	v_lshl_add_u64 v[52:53], v[52:53], 0, s[98:99]
	global_load_dwordx4 v[68:71], v[48:49], off
	v_lshl_add_u64 v[48:49], v[48:49], 0, s[100:101]
	global_load_dword v114, v[54:55], off offset:64
	global_load_dwordx2 v[100:101], v[52:53], off
	v_lshl_add_u64 v[52:53], v[52:53], 0, s[98:99]
	global_load_dwordx4 v[72:75], v[48:49], off
	v_lshl_add_u64 v[48:49], v[48:49], 0, s[100:101]
	global_load_dword v115, v[54:55], off offset:96
	global_load_dwordx2 v[102:103], v[52:53], off
	v_lshl_add_u64 v[52:53], v[52:53], 0, s[98:99]
	global_load_dwordx4 v[76:79], v[48:49], off
	v_lshl_add_u64 v[48:49], v[48:49], 0, s[100:101]
	global_load_dword v116, v[54:55], off offset:128
	global_load_dwordx2 v[104:105], v[52:53], off
	v_lshl_add_u64 v[52:53], v[52:53], 0, s[98:99]
	global_load_dwordx4 v[80:83], v[48:49], off
	v_lshl_add_u64 v[48:49], v[48:49], 0, s[100:101]
	global_load_dword v117, v[54:55], off offset:160
	global_load_dwordx2 v[106:107], v[52:53], off
	v_lshl_add_u64 v[52:53], v[52:53], 0, s[98:99]
	global_load_dwordx4 v[84:87], v[48:49], off
	v_lshl_add_u64 v[48:49], v[48:49], 0, s[100:101]
	global_load_dword v118, v[54:55], off offset:192
	global_load_dwordx2 v[108:109], v[52:53], off
	v_lshl_add_u64 v[52:53], v[52:53], 0, s[98:99]
	global_load_dwordx4 v[88:91], v[48:49], off
	v_lshl_add_u64 v[48:49], v[48:49], 0, s[100:101]
	global_load_dword v119, v[54:55], off offset:224
	global_load_dwordx2 v[110:111], v[52:53], off
	v_lshl_add_u64 v[52:53], v[52:53], 0, s[98:99]
	global_load_dwordx4 v[92:95], v[48:49], off
	v_lshl_add_u64 v[48:49], v[48:49], 0, s[100:101]
	s_mov_b32 s24, 0
	s_mov_b32 s25, -1
	ds_read_b128 v[18:21], v58
	s_waitcnt vmcnt(21)
	v_mov_b32_e32 v26, v112
	v_mov_b32_e32 v22, v96
	v_mov_b32_e32 v23, v97
	v_mov_b32_e32 v14, v64
	v_mov_b32_e32 v15, v65
	v_mov_b32_e32 v16, v66
	v_mov_b32_e32 v17, v67
	global_load_dword v112, v[54:55], off offset:256
	global_load_dwordx2 v[96:97], v[52:53], off
	v_lshl_add_u64 v[52:53], v[52:53], 0, s[98:99]
	global_load_dwordx4 v[64:67], v[48:49], off
	v_lshl_add_u64 v[48:49], v[48:49], 0, s[100:101]
	s_waitcnt lgkmcnt(0)
	v_mul_f32_e32 v27, v18, v26
	v_mul_f32_e32 v28, v19, v26
	v_mul_f32_e32 v20, v20, v26
	v_mul_f32_e32 v21, v21, v26
	s_nop 0
	v_lshlrev_b32_e32 v18, 16, v22
	v_mul_f32_e32 v26, 0xbfb8aa3b, v27
	v_and_b32_e32 v19, 0xffff0000, v22
	v_mul_f32_e32 v22, 0xbfb8aa3b, v28
	v_mul_f32_e32 v27, 0xbfb8aa3b, v20
	v_mul_f32_e32 v28, 0xbfb8aa3b, v21
	v_exp_f32_e32 v20, v26
	v_exp_f32_e32 v21, v22
	v_exp_f32_e32 v26, v27
	v_exp_f32_e32 v27, v28
	v_lshlrev_b32_e32 v22, 16, v23
	v_pk_add_f32 v[20:21], v[20:21], 1.0 op_sel_hi:[1,0]
	v_and_b32_e32 v23, 0xffff0000, v23
	v_div_scale_f32 v28, s[0:1], v21, v21, 1.0
	v_pk_add_f32 v[26:27], v[26:27], 1.0 op_sel_hi:[1,0]
	v_div_scale_f32 v30, s[0:1], v20, v20, 1.0
	v_rcp_f32_e32 v36, v28
	v_div_scale_f32 v32, s[6:7], v27, v27, 1.0
	v_rcp_f32_e32 v37, v30
	v_div_scale_f32 v34, s[8:9], v26, v26, 1.0
	v_rcp_f32_e32 v38, v32
	v_rcp_f32_e32 v39, v34
	v_fma_f32 v40, -v28, v36, 1.0
	v_div_scale_f32 v29, vcc, 1.0, v21, 1.0
	v_fma_f32 v41, -v30, v37, 1.0
	v_fmac_f32_e32 v36, v40, v36
	v_div_scale_f32 v31, s[0:1], 1.0, v20, 1.0
	v_fma_f32 v42, -v32, v38, 1.0
	v_fmac_f32_e32 v37, v41, v37
	v_mul_f32_e32 v40, v29, v36
	v_div_scale_f32 v33, s[6:7], 1.0, v27, 1.0
	v_fma_f32 v43, -v34, v39, 1.0
	v_fmac_f32_e32 v38, v42, v38
	v_mul_f32_e32 v41, v31, v37
	v_fma_f32 v44, -v28, v40, v29
	v_div_scale_f32 v35, s[8:9], 1.0, v26, 1.0
	v_fmac_f32_e32 v39, v43, v39
	v_mul_f32_e32 v42, v33, v38
	v_fma_f32 v45, -v30, v41, v31
	v_fmac_f32_e32 v40, v44, v36
	v_mul_f32_e32 v43, v35, v39
	v_fma_f32 v46, -v32, v42, v33
	v_fmac_f32_e32 v41, v45, v37
	v_fma_f32 v28, -v28, v40, v29
	v_fma_f32 v47, -v34, v43, v35
	v_fmac_f32_e32 v42, v46, v38
	v_fma_f32 v29, -v30, v41, v31
	v_div_fmas_f32 v28, v28, v36, v40
	s_mov_b64 vcc, s[0:1]
	v_fmac_f32_e32 v43, v47, v39
	v_fma_f32 v30, -v32, v42, v33
	v_div_fixup_f32 v21, v28, v21, 1.0
	v_div_fmas_f32 v28, v29, v37, v41
	s_mov_b64 vcc, s[6:7]
	v_fma_f32 v31, -v34, v43, v35
	v_div_fixup_f32 v20, v28, v20, 1.0
	v_div_fmas_f32 v28, v30, v38, v42
	s_mov_b64 vcc, s[8:9]
	s_nop 0
	v_pk_fma_f32 v[18:19], v[20:21], v[18:19], v[14:15]
	v_div_fmas_f32 v14, v31, v39, v43
	v_div_fixup_f32 v15, v28, v27, 1.0
	v_div_fixup_f32 v14, v14, v26, 1.0
	v_pk_mul_f32 v[26:27], v[18:19], v[18:19]
	v_pk_fma_f32 v[20:21], v[14:15], v[22:23], v[16:17]
	v_add_f32_e32 v16, v26, v27
	v_pk_mul_f32 v[14:15], v[20:21], v[20:21]
	global_store_dwordx4 v[50:51], v[18:21], off
	v_add_f32_e32 v14, v16, v14
	v_add_f32_e32 v14, v15, v14
	v_lshl_add_u64 v[50:51], v[50:51], 0, s[100:101]
	s_nop 0
	v_add_f32_dpp v15, v14, v14 quad_perm:[1,0,3,2] row_mask:0xf bank_mask:0xf
	s_nop 1
	v_add_f32_dpp v14, v15, v15 quad_perm:[2,3,0,1] row_mask:0xf bank_mask:0xf
	s_nop 1
	v_add_f32_dpp v15, v14, v14 row_half_mirror row_mask:0xf bank_mask:0xf
	s_nop 1
	v_add_f32_dpp v14, v15, v15 row_mirror row_mask:0xf bank_mask:0xf
	s_nop 1
	v_readlane_b32 s0, v14, 16
	v_readlane_b32 s1, v14, 48
	s_nop 1
	v_mov_b32_e32 v15, s0
	v_mov_b32_e32 v16, s1
	v_cndmask_b32_e64 v15, v15, v16, s[24:25]
	v_add_f32_e32 v14, v14, v15
	s_and_saveexec_b64 s[0:1], s[4:5]
	global_store_dword v[56:57], v14, off offset:0
	s_or_b64 exec, exec, s[0:1]
	ds_read_b128 v[18:21], v58 offset:4096
	s_waitcnt vmcnt(22)
	v_mov_b32_e32 v26, v113
	v_mov_b32_e32 v22, v98
	v_mov_b32_e32 v23, v99
	v_mov_b32_e32 v14, v68
	v_mov_b32_e32 v15, v69
	v_mov_b32_e32 v16, v70
	v_mov_b32_e32 v17, v71
	global_load_dword v113, v[54:55], off offset:288
	global_load_dwordx2 v[98:99], v[52:53], off
	v_lshl_add_u64 v[52:53], v[52:53], 0, s[98:99]
	global_load_dwordx4 v[68:71], v[48:49], off
	v_lshl_add_u64 v[48:49], v[48:49], 0, s[100:101]
	s_waitcnt lgkmcnt(0)
	v_mul_f32_e32 v27, v18, v26
	v_mul_f32_e32 v28, v19, v26
	v_mul_f32_e32 v20, v20, v26
	v_mul_f32_e32 v21, v21, v26
	s_nop 0
	v_lshlrev_b32_e32 v18, 16, v22
	v_mul_f32_e32 v26, 0xbfb8aa3b, v27
	v_and_b32_e32 v19, 0xffff0000, v22
	v_mul_f32_e32 v22, 0xbfb8aa3b, v28
	v_mul_f32_e32 v27, 0xbfb8aa3b, v20
	v_mul_f32_e32 v28, 0xbfb8aa3b, v21
	v_exp_f32_e32 v20, v26
	v_exp_f32_e32 v21, v22
	v_exp_f32_e32 v26, v27
	v_exp_f32_e32 v27, v28
	v_lshlrev_b32_e32 v22, 16, v23
	v_pk_add_f32 v[20:21], v[20:21], 1.0 op_sel_hi:[1,0]
	v_and_b32_e32 v23, 0xffff0000, v23
	v_div_scale_f32 v28, s[0:1], v21, v21, 1.0
	v_pk_add_f32 v[26:27], v[26:27], 1.0 op_sel_hi:[1,0]
	v_div_scale_f32 v30, s[0:1], v20, v20, 1.0
	v_rcp_f32_e32 v36, v28
	v_div_scale_f32 v32, s[6:7], v27, v27, 1.0
	v_rcp_f32_e32 v37, v30
	v_div_scale_f32 v34, s[8:9], v26, v26, 1.0
	v_rcp_f32_e32 v38, v32
	v_rcp_f32_e32 v39, v34
	v_fma_f32 v40, -v28, v36, 1.0
	v_div_scale_f32 v29, vcc, 1.0, v21, 1.0
	v_fma_f32 v41, -v30, v37, 1.0
	v_fmac_f32_e32 v36, v40, v36
	v_div_scale_f32 v31, s[0:1], 1.0, v20, 1.0
	v_fma_f32 v42, -v32, v38, 1.0
	v_fmac_f32_e32 v37, v41, v37
	v_mul_f32_e32 v40, v29, v36
	v_div_scale_f32 v33, s[6:7], 1.0, v27, 1.0
	v_fma_f32 v43, -v34, v39, 1.0
	v_fmac_f32_e32 v38, v42, v38
	v_mul_f32_e32 v41, v31, v37
	v_fma_f32 v44, -v28, v40, v29
	v_div_scale_f32 v35, s[8:9], 1.0, v26, 1.0
	v_fmac_f32_e32 v39, v43, v39
	v_mul_f32_e32 v42, v33, v38
	v_fma_f32 v45, -v30, v41, v31
	v_fmac_f32_e32 v40, v44, v36
	v_mul_f32_e32 v43, v35, v39
	v_fma_f32 v46, -v32, v42, v33
	v_fmac_f32_e32 v41, v45, v37
	v_fma_f32 v28, -v28, v40, v29
	v_fma_f32 v47, -v34, v43, v35
	v_fmac_f32_e32 v42, v46, v38
	v_fma_f32 v29, -v30, v41, v31
	v_div_fmas_f32 v28, v28, v36, v40
	s_mov_b64 vcc, s[0:1]
	v_fmac_f32_e32 v43, v47, v39
	v_fma_f32 v30, -v32, v42, v33
	v_div_fixup_f32 v21, v28, v21, 1.0
	v_div_fmas_f32 v28, v29, v37, v41
	s_mov_b64 vcc, s[6:7]
	v_fma_f32 v31, -v34, v43, v35
	v_div_fixup_f32 v20, v28, v20, 1.0
	v_div_fmas_f32 v28, v30, v38, v42
	s_mov_b64 vcc, s[8:9]
	s_nop 0
	v_pk_fma_f32 v[18:19], v[20:21], v[18:19], v[14:15]
	v_div_fmas_f32 v14, v31, v39, v43
	v_div_fixup_f32 v15, v28, v27, 1.0
	v_div_fixup_f32 v14, v14, v26, 1.0
	v_pk_mul_f32 v[26:27], v[18:19], v[18:19]
	v_pk_fma_f32 v[20:21], v[14:15], v[22:23], v[16:17]
	v_add_f32_e32 v16, v26, v27
	v_pk_mul_f32 v[14:15], v[20:21], v[20:21]
	global_store_dwordx4 v[50:51], v[18:21], off
	v_add_f32_e32 v14, v16, v14
	v_add_f32_e32 v14, v15, v14
	v_lshl_add_u64 v[50:51], v[50:51], 0, s[100:101]
	s_nop 0
	v_add_f32_dpp v15, v14, v14 quad_perm:[1,0,3,2] row_mask:0xf bank_mask:0xf
	s_nop 1
	v_add_f32_dpp v14, v15, v15 quad_perm:[2,3,0,1] row_mask:0xf bank_mask:0xf
	s_nop 1
	v_add_f32_dpp v15, v14, v14 row_half_mirror row_mask:0xf bank_mask:0xf
	s_nop 1
	v_add_f32_dpp v14, v15, v15 row_mirror row_mask:0xf bank_mask:0xf
	s_nop 1
	v_readlane_b32 s0, v14, 16
	v_readlane_b32 s1, v14, 48
	s_nop 1
	v_mov_b32_e32 v15, s0
	v_mov_b32_e32 v16, s1
	v_cndmask_b32_e64 v15, v15, v16, s[24:25]
	v_add_f32_e32 v14, v14, v15
	s_and_saveexec_b64 s[0:1], s[4:5]
	global_store_dword v[56:57], v14, off offset:32
	s_or_b64 exec, exec, s[0:1]
	ds_read_b128 v[18:21], v58 offset:8192
	s_waitcnt vmcnt(23)
	v_mov_b32_e32 v26, v114
	v_mov_b32_e32 v22, v100
	v_mov_b32_e32 v23, v101
	v_mov_b32_e32 v14, v72
	v_mov_b32_e32 v15, v73
	v_mov_b32_e32 v16, v74
	v_mov_b32_e32 v17, v75
	global_load_dword v114, v[54:55], off offset:320
	global_load_dwordx2 v[100:101], v[52:53], off
	v_lshl_add_u64 v[52:53], v[52:53], 0, s[98:99]
	global_load_dwordx4 v[72:75], v[48:49], off
	v_lshl_add_u64 v[48:49], v[48:49], 0, s[100:101]
	s_waitcnt lgkmcnt(0)
	v_mul_f32_e32 v27, v18, v26
	v_mul_f32_e32 v28, v19, v26
	v_mul_f32_e32 v20, v20, v26
	v_mul_f32_e32 v21, v21, v26
	s_nop 0
	v_lshlrev_b32_e32 v18, 16, v22
	v_mul_f32_e32 v26, 0xbfb8aa3b, v27
	v_and_b32_e32 v19, 0xffff0000, v22
	v_mul_f32_e32 v22, 0xbfb8aa3b, v28
	v_mul_f32_e32 v27, 0xbfb8aa3b, v20
	v_mul_f32_e32 v28, 0xbfb8aa3b, v21
	v_exp_f32_e32 v20, v26
	v_exp_f32_e32 v21, v22
	v_exp_f32_e32 v26, v27
	v_exp_f32_e32 v27, v28
	v_lshlrev_b32_e32 v22, 16, v23
	v_pk_add_f32 v[20:21], v[20:21], 1.0 op_sel_hi:[1,0]
	v_and_b32_e32 v23, 0xffff0000, v23
	v_div_scale_f32 v28, s[0:1], v21, v21, 1.0
	v_pk_add_f32 v[26:27], v[26:27], 1.0 op_sel_hi:[1,0]
	v_div_scale_f32 v30, s[0:1], v20, v20, 1.0
	v_rcp_f32_e32 v36, v28
	v_div_scale_f32 v32, s[6:7], v27, v27, 1.0
	v_rcp_f32_e32 v37, v30
	v_div_scale_f32 v34, s[8:9], v26, v26, 1.0
	v_rcp_f32_e32 v38, v32
	v_rcp_f32_e32 v39, v34
	v_fma_f32 v40, -v28, v36, 1.0
	v_div_scale_f32 v29, vcc, 1.0, v21, 1.0
	v_fma_f32 v41, -v30, v37, 1.0
	v_fmac_f32_e32 v36, v40, v36
	v_div_scale_f32 v31, s[0:1], 1.0, v20, 1.0
	v_fma_f32 v42, -v32, v38, 1.0
	v_fmac_f32_e32 v37, v41, v37
	v_mul_f32_e32 v40, v29, v36
	v_div_scale_f32 v33, s[6:7], 1.0, v27, 1.0
	v_fma_f32 v43, -v34, v39, 1.0
	v_fmac_f32_e32 v38, v42, v38
	v_mul_f32_e32 v41, v31, v37
	v_fma_f32 v44, -v28, v40, v29
	v_div_scale_f32 v35, s[8:9], 1.0, v26, 1.0
	v_fmac_f32_e32 v39, v43, v39
	v_mul_f32_e32 v42, v33, v38
	v_fma_f32 v45, -v30, v41, v31
	v_fmac_f32_e32 v40, v44, v36
	v_mul_f32_e32 v43, v35, v39
	v_fma_f32 v46, -v32, v42, v33
	v_fmac_f32_e32 v41, v45, v37
	v_fma_f32 v28, -v28, v40, v29
	v_fma_f32 v47, -v34, v43, v35
	v_fmac_f32_e32 v42, v46, v38
	v_fma_f32 v29, -v30, v41, v31
	v_div_fmas_f32 v28, v28, v36, v40
	s_mov_b64 vcc, s[0:1]
	v_fmac_f32_e32 v43, v47, v39
	v_fma_f32 v30, -v32, v42, v33
	v_div_fixup_f32 v21, v28, v21, 1.0
	v_div_fmas_f32 v28, v29, v37, v41
	s_mov_b64 vcc, s[6:7]
	v_fma_f32 v31, -v34, v43, v35
	v_div_fixup_f32 v20, v28, v20, 1.0
	v_div_fmas_f32 v28, v30, v38, v42
	s_mov_b64 vcc, s[8:9]
	s_nop 0
	v_pk_fma_f32 v[18:19], v[20:21], v[18:19], v[14:15]
	v_div_fmas_f32 v14, v31, v39, v43
	v_div_fixup_f32 v15, v28, v27, 1.0
	v_div_fixup_f32 v14, v14, v26, 1.0
	v_pk_mul_f32 v[26:27], v[18:19], v[18:19]
	v_pk_fma_f32 v[20:21], v[14:15], v[22:23], v[16:17]
	v_add_f32_e32 v16, v26, v27
	v_pk_mul_f32 v[14:15], v[20:21], v[20:21]
	global_store_dwordx4 v[50:51], v[18:21], off
	v_add_f32_e32 v14, v16, v14
	v_add_f32_e32 v14, v15, v14
	v_lshl_add_u64 v[50:51], v[50:51], 0, s[100:101]
	s_nop 0
	v_add_f32_dpp v15, v14, v14 quad_perm:[1,0,3,2] row_mask:0xf bank_mask:0xf
	s_nop 1
	v_add_f32_dpp v14, v15, v15 quad_perm:[2,3,0,1] row_mask:0xf bank_mask:0xf
	s_nop 1
	v_add_f32_dpp v15, v14, v14 row_half_mirror row_mask:0xf bank_mask:0xf
	s_nop 1
	v_add_f32_dpp v14, v15, v15 row_mirror row_mask:0xf bank_mask:0xf
	s_nop 1
	v_readlane_b32 s0, v14, 16
	v_readlane_b32 s1, v14, 48
	s_nop 1
	v_mov_b32_e32 v15, s0
	v_mov_b32_e32 v16, s1
	v_cndmask_b32_e64 v15, v15, v16, s[24:25]
	v_add_f32_e32 v14, v14, v15
	s_and_saveexec_b64 s[0:1], s[4:5]
	global_store_dword v[56:57], v14, off offset:64
	s_or_b64 exec, exec, s[0:1]
	ds_read_b128 v[18:21], v58 offset:12288
	s_waitcnt vmcnt(24)
	v_mov_b32_e32 v26, v115
	v_mov_b32_e32 v22, v102
	v_mov_b32_e32 v23, v103
	v_mov_b32_e32 v14, v76
	v_mov_b32_e32 v15, v77
	v_mov_b32_e32 v16, v78
	v_mov_b32_e32 v17, v79
	global_load_dword v115, v[54:55], off offset:352
	global_load_dwordx2 v[102:103], v[52:53], off
	v_lshl_add_u64 v[52:53], v[52:53], 0, s[98:99]
	global_load_dwordx4 v[76:79], v[48:49], off
	v_lshl_add_u64 v[48:49], v[48:49], 0, s[100:101]
	s_waitcnt lgkmcnt(0)
	v_mul_f32_e32 v27, v18, v26
	v_mul_f32_e32 v28, v19, v26
	v_mul_f32_e32 v20, v20, v26
	v_mul_f32_e32 v21, v21, v26
	s_nop 0
	v_lshlrev_b32_e32 v18, 16, v22
	v_mul_f32_e32 v26, 0xbfb8aa3b, v27
	v_and_b32_e32 v19, 0xffff0000, v22
	v_mul_f32_e32 v22, 0xbfb8aa3b, v28
	v_mul_f32_e32 v27, 0xbfb8aa3b, v20
	v_mul_f32_e32 v28, 0xbfb8aa3b, v21
	v_exp_f32_e32 v20, v26
	v_exp_f32_e32 v21, v22
	v_exp_f32_e32 v26, v27
	v_exp_f32_e32 v27, v28
	v_lshlrev_b32_e32 v22, 16, v23
	v_pk_add_f32 v[20:21], v[20:21], 1.0 op_sel_hi:[1,0]
	v_and_b32_e32 v23, 0xffff0000, v23
	v_div_scale_f32 v28, s[0:1], v21, v21, 1.0
	v_pk_add_f32 v[26:27], v[26:27], 1.0 op_sel_hi:[1,0]
	v_div_scale_f32 v30, s[0:1], v20, v20, 1.0
	v_rcp_f32_e32 v36, v28
	v_div_scale_f32 v32, s[6:7], v27, v27, 1.0
	v_rcp_f32_e32 v37, v30
	v_div_scale_f32 v34, s[8:9], v26, v26, 1.0
	v_rcp_f32_e32 v38, v32
	v_rcp_f32_e32 v39, v34
	v_fma_f32 v40, -v28, v36, 1.0
	v_div_scale_f32 v29, vcc, 1.0, v21, 1.0
	v_fma_f32 v41, -v30, v37, 1.0
	v_fmac_f32_e32 v36, v40, v36
	v_div_scale_f32 v31, s[0:1], 1.0, v20, 1.0
	v_fma_f32 v42, -v32, v38, 1.0
	v_fmac_f32_e32 v37, v41, v37
	v_mul_f32_e32 v40, v29, v36
	v_div_scale_f32 v33, s[6:7], 1.0, v27, 1.0
	v_fma_f32 v43, -v34, v39, 1.0
	v_fmac_f32_e32 v38, v42, v38
	v_mul_f32_e32 v41, v31, v37
	v_fma_f32 v44, -v28, v40, v29
	v_div_scale_f32 v35, s[8:9], 1.0, v26, 1.0
	v_fmac_f32_e32 v39, v43, v39
	v_mul_f32_e32 v42, v33, v38
	v_fma_f32 v45, -v30, v41, v31
	v_fmac_f32_e32 v40, v44, v36
	v_mul_f32_e32 v43, v35, v39
	v_fma_f32 v46, -v32, v42, v33
	v_fmac_f32_e32 v41, v45, v37
	v_fma_f32 v28, -v28, v40, v29
	v_fma_f32 v47, -v34, v43, v35
	v_fmac_f32_e32 v42, v46, v38
	v_fma_f32 v29, -v30, v41, v31
	v_div_fmas_f32 v28, v28, v36, v40
	s_mov_b64 vcc, s[0:1]
	v_fmac_f32_e32 v43, v47, v39
	v_fma_f32 v30, -v32, v42, v33
	v_div_fixup_f32 v21, v28, v21, 1.0
	v_div_fmas_f32 v28, v29, v37, v41
	s_mov_b64 vcc, s[6:7]
	v_fma_f32 v31, -v34, v43, v35
	v_div_fixup_f32 v20, v28, v20, 1.0
	v_div_fmas_f32 v28, v30, v38, v42
	s_mov_b64 vcc, s[8:9]
	s_nop 0
	v_pk_fma_f32 v[18:19], v[20:21], v[18:19], v[14:15]
	v_div_fmas_f32 v14, v31, v39, v43
	v_div_fixup_f32 v15, v28, v27, 1.0
	v_div_fixup_f32 v14, v14, v26, 1.0
	v_pk_mul_f32 v[26:27], v[18:19], v[18:19]
	v_pk_fma_f32 v[20:21], v[14:15], v[22:23], v[16:17]
	v_add_f32_e32 v16, v26, v27
	v_pk_mul_f32 v[14:15], v[20:21], v[20:21]
	global_store_dwordx4 v[50:51], v[18:21], off
	v_add_f32_e32 v14, v16, v14
	v_add_f32_e32 v14, v15, v14
	v_lshl_add_u64 v[50:51], v[50:51], 0, s[100:101]
	s_nop 0
	v_add_f32_dpp v15, v14, v14 quad_perm:[1,0,3,2] row_mask:0xf bank_mask:0xf
	s_nop 1
	v_add_f32_dpp v14, v15, v15 quad_perm:[2,3,0,1] row_mask:0xf bank_mask:0xf
	s_nop 1
	v_add_f32_dpp v15, v14, v14 row_half_mirror row_mask:0xf bank_mask:0xf
	s_nop 1
	v_add_f32_dpp v14, v15, v15 row_mirror row_mask:0xf bank_mask:0xf
	s_nop 1
	v_readlane_b32 s0, v14, 16
	v_readlane_b32 s1, v14, 48
	s_nop 1
	v_mov_b32_e32 v15, s0
	v_mov_b32_e32 v16, s1
	v_cndmask_b32_e64 v15, v15, v16, s[24:25]
	v_add_f32_e32 v14, v14, v15
	s_and_saveexec_b64 s[0:1], s[4:5]
	global_store_dword v[56:57], v14, off offset:96
	s_or_b64 exec, exec, s[0:1]
	ds_read_b128 v[18:21], v58 offset:16384
	s_waitcnt vmcnt(25)
	v_mov_b32_e32 v26, v116
	v_mov_b32_e32 v22, v104
	v_mov_b32_e32 v23, v105
	v_mov_b32_e32 v14, v80
	v_mov_b32_e32 v15, v81
	v_mov_b32_e32 v16, v82
	v_mov_b32_e32 v17, v83
	global_load_dword v116, v[54:55], off offset:384
	global_load_dwordx2 v[104:105], v[52:53], off
	v_lshl_add_u64 v[52:53], v[52:53], 0, s[98:99]
	global_load_dwordx4 v[80:83], v[48:49], off
	v_lshl_add_u64 v[48:49], v[48:49], 0, s[100:101]
	s_waitcnt lgkmcnt(0)
	v_mul_f32_e32 v27, v18, v26
	v_mul_f32_e32 v28, v19, v26
	v_mul_f32_e32 v20, v20, v26
	v_mul_f32_e32 v21, v21, v26
	s_nop 0
	v_lshlrev_b32_e32 v18, 16, v22
	v_mul_f32_e32 v26, 0xbfb8aa3b, v27
	v_and_b32_e32 v19, 0xffff0000, v22
	v_mul_f32_e32 v22, 0xbfb8aa3b, v28
	v_mul_f32_e32 v27, 0xbfb8aa3b, v20
	v_mul_f32_e32 v28, 0xbfb8aa3b, v21
	v_exp_f32_e32 v20, v26
	v_exp_f32_e32 v21, v22
	v_exp_f32_e32 v26, v27
	v_exp_f32_e32 v27, v28
	v_lshlrev_b32_e32 v22, 16, v23
	v_pk_add_f32 v[20:21], v[20:21], 1.0 op_sel_hi:[1,0]
	v_and_b32_e32 v23, 0xffff0000, v23
	v_div_scale_f32 v28, s[0:1], v21, v21, 1.0
	v_pk_add_f32 v[26:27], v[26:27], 1.0 op_sel_hi:[1,0]
	v_div_scale_f32 v30, s[0:1], v20, v20, 1.0
	v_rcp_f32_e32 v36, v28
	v_div_scale_f32 v32, s[6:7], v27, v27, 1.0
	v_rcp_f32_e32 v37, v30
	v_div_scale_f32 v34, s[8:9], v26, v26, 1.0
	v_rcp_f32_e32 v38, v32
	v_rcp_f32_e32 v39, v34
	v_fma_f32 v40, -v28, v36, 1.0
	v_div_scale_f32 v29, vcc, 1.0, v21, 1.0
	v_fma_f32 v41, -v30, v37, 1.0
	v_fmac_f32_e32 v36, v40, v36
	v_div_scale_f32 v31, s[0:1], 1.0, v20, 1.0
	v_fma_f32 v42, -v32, v38, 1.0
	v_fmac_f32_e32 v37, v41, v37
	v_mul_f32_e32 v40, v29, v36
	v_div_scale_f32 v33, s[6:7], 1.0, v27, 1.0
	v_fma_f32 v43, -v34, v39, 1.0
	v_fmac_f32_e32 v38, v42, v38
	v_mul_f32_e32 v41, v31, v37
	v_fma_f32 v44, -v28, v40, v29
	v_div_scale_f32 v35, s[8:9], 1.0, v26, 1.0
	v_fmac_f32_e32 v39, v43, v39
	v_mul_f32_e32 v42, v33, v38
	v_fma_f32 v45, -v30, v41, v31
	v_fmac_f32_e32 v40, v44, v36
	v_mul_f32_e32 v43, v35, v39
	v_fma_f32 v46, -v32, v42, v33
	v_fmac_f32_e32 v41, v45, v37
	v_fma_f32 v28, -v28, v40, v29
	v_fma_f32 v47, -v34, v43, v35
	v_fmac_f32_e32 v42, v46, v38
	v_fma_f32 v29, -v30, v41, v31
	v_div_fmas_f32 v28, v28, v36, v40
	s_mov_b64 vcc, s[0:1]
	v_fmac_f32_e32 v43, v47, v39
	v_fma_f32 v30, -v32, v42, v33
	v_div_fixup_f32 v21, v28, v21, 1.0
	v_div_fmas_f32 v28, v29, v37, v41
	s_mov_b64 vcc, s[6:7]
	v_fma_f32 v31, -v34, v43, v35
	v_div_fixup_f32 v20, v28, v20, 1.0
	v_div_fmas_f32 v28, v30, v38, v42
	s_mov_b64 vcc, s[8:9]
	s_nop 0
	v_pk_fma_f32 v[18:19], v[20:21], v[18:19], v[14:15]
	v_div_fmas_f32 v14, v31, v39, v43
	v_div_fixup_f32 v15, v28, v27, 1.0
	v_div_fixup_f32 v14, v14, v26, 1.0
	v_pk_mul_f32 v[26:27], v[18:19], v[18:19]
	v_pk_fma_f32 v[20:21], v[14:15], v[22:23], v[16:17]
	v_add_f32_e32 v16, v26, v27
	v_pk_mul_f32 v[14:15], v[20:21], v[20:21]
	global_store_dwordx4 v[50:51], v[18:21], off
	v_add_f32_e32 v14, v16, v14
	v_add_f32_e32 v14, v15, v14
	v_lshl_add_u64 v[50:51], v[50:51], 0, s[100:101]
	s_nop 0
	v_add_f32_dpp v15, v14, v14 quad_perm:[1,0,3,2] row_mask:0xf bank_mask:0xf
	s_nop 1
	v_add_f32_dpp v14, v15, v15 quad_perm:[2,3,0,1] row_mask:0xf bank_mask:0xf
	s_nop 1
	v_add_f32_dpp v15, v14, v14 row_half_mirror row_mask:0xf bank_mask:0xf
	s_nop 1
	v_add_f32_dpp v14, v15, v15 row_mirror row_mask:0xf bank_mask:0xf
	s_nop 1
	v_readlane_b32 s0, v14, 16
	v_readlane_b32 s1, v14, 48
	s_nop 1
	v_mov_b32_e32 v15, s0
	v_mov_b32_e32 v16, s1
	v_cndmask_b32_e64 v15, v15, v16, s[24:25]
	v_add_f32_e32 v14, v14, v15
	s_and_saveexec_b64 s[0:1], s[4:5]
	global_store_dword v[56:57], v14, off offset:128
	s_or_b64 exec, exec, s[0:1]
	ds_read_b128 v[18:21], v58 offset:20480
	s_waitcnt vmcnt(26)
	v_mov_b32_e32 v26, v117
	v_mov_b32_e32 v22, v106
	v_mov_b32_e32 v23, v107
	v_mov_b32_e32 v14, v84
	v_mov_b32_e32 v15, v85
	v_mov_b32_e32 v16, v86
	v_mov_b32_e32 v17, v87
	global_load_dword v117, v[54:55], off offset:416
	global_load_dwordx2 v[106:107], v[52:53], off
	v_lshl_add_u64 v[52:53], v[52:53], 0, s[98:99]
	global_load_dwordx4 v[84:87], v[48:49], off
	v_lshl_add_u64 v[48:49], v[48:49], 0, s[100:101]
	s_waitcnt lgkmcnt(0)
	v_mul_f32_e32 v27, v18, v26
	v_mul_f32_e32 v28, v19, v26
	v_mul_f32_e32 v20, v20, v26
	v_mul_f32_e32 v21, v21, v26
	s_nop 0
	v_lshlrev_b32_e32 v18, 16, v22
	v_mul_f32_e32 v26, 0xbfb8aa3b, v27
	v_and_b32_e32 v19, 0xffff0000, v22
	v_mul_f32_e32 v22, 0xbfb8aa3b, v28
	v_mul_f32_e32 v27, 0xbfb8aa3b, v20
	v_mul_f32_e32 v28, 0xbfb8aa3b, v21
	v_exp_f32_e32 v20, v26
	v_exp_f32_e32 v21, v22
	v_exp_f32_e32 v26, v27
	v_exp_f32_e32 v27, v28
	v_lshlrev_b32_e32 v22, 16, v23
	v_pk_add_f32 v[20:21], v[20:21], 1.0 op_sel_hi:[1,0]
	v_and_b32_e32 v23, 0xffff0000, v23
	v_div_scale_f32 v28, s[0:1], v21, v21, 1.0
	v_pk_add_f32 v[26:27], v[26:27], 1.0 op_sel_hi:[1,0]
	v_div_scale_f32 v30, s[0:1], v20, v20, 1.0
	v_rcp_f32_e32 v36, v28
	v_div_scale_f32 v32, s[6:7], v27, v27, 1.0
	v_rcp_f32_e32 v37, v30
	v_div_scale_f32 v34, s[8:9], v26, v26, 1.0
	v_rcp_f32_e32 v38, v32
	v_rcp_f32_e32 v39, v34
	v_fma_f32 v40, -v28, v36, 1.0
	v_div_scale_f32 v29, vcc, 1.0, v21, 1.0
	v_fma_f32 v41, -v30, v37, 1.0
	v_fmac_f32_e32 v36, v40, v36
	v_div_scale_f32 v31, s[0:1], 1.0, v20, 1.0
	v_fma_f32 v42, -v32, v38, 1.0
	v_fmac_f32_e32 v37, v41, v37
	v_mul_f32_e32 v40, v29, v36
	v_div_scale_f32 v33, s[6:7], 1.0, v27, 1.0
	v_fma_f32 v43, -v34, v39, 1.0
	v_fmac_f32_e32 v38, v42, v38
	v_mul_f32_e32 v41, v31, v37
	v_fma_f32 v44, -v28, v40, v29
	v_div_scale_f32 v35, s[8:9], 1.0, v26, 1.0
	v_fmac_f32_e32 v39, v43, v39
	v_mul_f32_e32 v42, v33, v38
	v_fma_f32 v45, -v30, v41, v31
	v_fmac_f32_e32 v40, v44, v36
	v_mul_f32_e32 v43, v35, v39
	v_fma_f32 v46, -v32, v42, v33
	v_fmac_f32_e32 v41, v45, v37
	v_fma_f32 v28, -v28, v40, v29
	v_fma_f32 v47, -v34, v43, v35
	v_fmac_f32_e32 v42, v46, v38
	v_fma_f32 v29, -v30, v41, v31
	v_div_fmas_f32 v28, v28, v36, v40
	s_mov_b64 vcc, s[0:1]
	v_fmac_f32_e32 v43, v47, v39
	v_fma_f32 v30, -v32, v42, v33
	v_div_fixup_f32 v21, v28, v21, 1.0
	v_div_fmas_f32 v28, v29, v37, v41
	s_mov_b64 vcc, s[6:7]
	v_fma_f32 v31, -v34, v43, v35
	v_div_fixup_f32 v20, v28, v20, 1.0
	v_div_fmas_f32 v28, v30, v38, v42
	s_mov_b64 vcc, s[8:9]
	s_nop 0
	v_pk_fma_f32 v[18:19], v[20:21], v[18:19], v[14:15]
	v_div_fmas_f32 v14, v31, v39, v43
	v_div_fixup_f32 v15, v28, v27, 1.0
	v_div_fixup_f32 v14, v14, v26, 1.0
	v_pk_mul_f32 v[26:27], v[18:19], v[18:19]
	v_pk_fma_f32 v[20:21], v[14:15], v[22:23], v[16:17]
	v_add_f32_e32 v16, v26, v27
	v_pk_mul_f32 v[14:15], v[20:21], v[20:21]
	global_store_dwordx4 v[50:51], v[18:21], off
	v_add_f32_e32 v14, v16, v14
	v_add_f32_e32 v14, v15, v14
	v_lshl_add_u64 v[50:51], v[50:51], 0, s[100:101]
	s_nop 0
	v_add_f32_dpp v15, v14, v14 quad_perm:[1,0,3,2] row_mask:0xf bank_mask:0xf
	s_nop 1
	v_add_f32_dpp v14, v15, v15 quad_perm:[2,3,0,1] row_mask:0xf bank_mask:0xf
	s_nop 1
	v_add_f32_dpp v15, v14, v14 row_half_mirror row_mask:0xf bank_mask:0xf
	s_nop 1
	v_add_f32_dpp v14, v15, v15 row_mirror row_mask:0xf bank_mask:0xf
	s_nop 1
	v_readlane_b32 s0, v14, 16
	v_readlane_b32 s1, v14, 48
	s_nop 1
	v_mov_b32_e32 v15, s0
	v_mov_b32_e32 v16, s1
	v_cndmask_b32_e64 v15, v15, v16, s[24:25]
	v_add_f32_e32 v14, v14, v15
	s_and_saveexec_b64 s[0:1], s[4:5]
	global_store_dword v[56:57], v14, off offset:160
	s_or_b64 exec, exec, s[0:1]
	ds_read_b128 v[18:21], v58 offset:24576
	s_waitcnt vmcnt(27)
	v_mov_b32_e32 v26, v118
	v_mov_b32_e32 v22, v108
	v_mov_b32_e32 v23, v109
	v_mov_b32_e32 v14, v88
	v_mov_b32_e32 v15, v89
	v_mov_b32_e32 v16, v90
	v_mov_b32_e32 v17, v91
	global_load_dword v118, v[54:55], off offset:448
	global_load_dwordx2 v[108:109], v[52:53], off
	v_lshl_add_u64 v[52:53], v[52:53], 0, s[98:99]
	global_load_dwordx4 v[88:91], v[48:49], off
	v_lshl_add_u64 v[48:49], v[48:49], 0, s[100:101]
	s_waitcnt lgkmcnt(0)
	v_mul_f32_e32 v27, v18, v26
	v_mul_f32_e32 v28, v19, v26
	v_mul_f32_e32 v20, v20, v26
	v_mul_f32_e32 v21, v21, v26
	s_nop 0
	v_lshlrev_b32_e32 v18, 16, v22
	v_mul_f32_e32 v26, 0xbfb8aa3b, v27
	v_and_b32_e32 v19, 0xffff0000, v22
	v_mul_f32_e32 v22, 0xbfb8aa3b, v28
	v_mul_f32_e32 v27, 0xbfb8aa3b, v20
	v_mul_f32_e32 v28, 0xbfb8aa3b, v21
	v_exp_f32_e32 v20, v26
	v_exp_f32_e32 v21, v22
	v_exp_f32_e32 v26, v27
	v_exp_f32_e32 v27, v28
	v_lshlrev_b32_e32 v22, 16, v23
	v_pk_add_f32 v[20:21], v[20:21], 1.0 op_sel_hi:[1,0]
	v_and_b32_e32 v23, 0xffff0000, v23
	v_div_scale_f32 v28, s[0:1], v21, v21, 1.0
	v_pk_add_f32 v[26:27], v[26:27], 1.0 op_sel_hi:[1,0]
	v_div_scale_f32 v30, s[0:1], v20, v20, 1.0
	v_rcp_f32_e32 v36, v28
	v_div_scale_f32 v32, s[6:7], v27, v27, 1.0
	v_rcp_f32_e32 v37, v30
	v_div_scale_f32 v34, s[8:9], v26, v26, 1.0
	v_rcp_f32_e32 v38, v32
	v_rcp_f32_e32 v39, v34
	v_fma_f32 v40, -v28, v36, 1.0
	v_div_scale_f32 v29, vcc, 1.0, v21, 1.0
	v_fma_f32 v41, -v30, v37, 1.0
	v_fmac_f32_e32 v36, v40, v36
	v_div_scale_f32 v31, s[0:1], 1.0, v20, 1.0
	v_fma_f32 v42, -v32, v38, 1.0
	v_fmac_f32_e32 v37, v41, v37
	v_mul_f32_e32 v40, v29, v36
	v_div_scale_f32 v33, s[6:7], 1.0, v27, 1.0
	v_fma_f32 v43, -v34, v39, 1.0
	v_fmac_f32_e32 v38, v42, v38
	v_mul_f32_e32 v41, v31, v37
	v_fma_f32 v44, -v28, v40, v29
	v_div_scale_f32 v35, s[8:9], 1.0, v26, 1.0
	v_fmac_f32_e32 v39, v43, v39
	v_mul_f32_e32 v42, v33, v38
	v_fma_f32 v45, -v30, v41, v31
	v_fmac_f32_e32 v40, v44, v36
	v_mul_f32_e32 v43, v35, v39
	v_fma_f32 v46, -v32, v42, v33
	v_fmac_f32_e32 v41, v45, v37
	v_fma_f32 v28, -v28, v40, v29
	v_fma_f32 v47, -v34, v43, v35
	v_fmac_f32_e32 v42, v46, v38
	v_fma_f32 v29, -v30, v41, v31
	v_div_fmas_f32 v28, v28, v36, v40
	s_mov_b64 vcc, s[0:1]
	v_fmac_f32_e32 v43, v47, v39
	v_fma_f32 v30, -v32, v42, v33
	v_div_fixup_f32 v21, v28, v21, 1.0
	v_div_fmas_f32 v28, v29, v37, v41
	s_mov_b64 vcc, s[6:7]
	v_fma_f32 v31, -v34, v43, v35
	v_div_fixup_f32 v20, v28, v20, 1.0
	v_div_fmas_f32 v28, v30, v38, v42
	s_mov_b64 vcc, s[8:9]
	s_nop 0
	v_pk_fma_f32 v[18:19], v[20:21], v[18:19], v[14:15]
	v_div_fmas_f32 v14, v31, v39, v43
	v_div_fixup_f32 v15, v28, v27, 1.0
	v_div_fixup_f32 v14, v14, v26, 1.0
	v_pk_mul_f32 v[26:27], v[18:19], v[18:19]
	v_pk_fma_f32 v[20:21], v[14:15], v[22:23], v[16:17]
	v_add_f32_e32 v16, v26, v27
	v_pk_mul_f32 v[14:15], v[20:21], v[20:21]
	global_store_dwordx4 v[50:51], v[18:21], off
	v_add_f32_e32 v14, v16, v14
	v_add_f32_e32 v14, v15, v14
	v_lshl_add_u64 v[50:51], v[50:51], 0, s[100:101]
	s_nop 0
	v_add_f32_dpp v15, v14, v14 quad_perm:[1,0,3,2] row_mask:0xf bank_mask:0xf
	s_nop 1
	v_add_f32_dpp v14, v15, v15 quad_perm:[2,3,0,1] row_mask:0xf bank_mask:0xf
	s_nop 1
	v_add_f32_dpp v15, v14, v14 row_half_mirror row_mask:0xf bank_mask:0xf
	s_nop 1
	v_add_f32_dpp v14, v15, v15 row_mirror row_mask:0xf bank_mask:0xf
	s_nop 1
	v_readlane_b32 s0, v14, 16
	v_readlane_b32 s1, v14, 48
	s_nop 1
	v_mov_b32_e32 v15, s0
	v_mov_b32_e32 v16, s1
	v_cndmask_b32_e64 v15, v15, v16, s[24:25]
	v_add_f32_e32 v14, v14, v15
	s_and_saveexec_b64 s[0:1], s[4:5]
	global_store_dword v[56:57], v14, off offset:192
	s_or_b64 exec, exec, s[0:1]
	ds_read_b128 v[18:21], v58 offset:28672
	s_waitcnt vmcnt(28)
	v_mov_b32_e32 v26, v119
	v_mov_b32_e32 v22, v110
	v_mov_b32_e32 v23, v111
	v_mov_b32_e32 v14, v92
	v_mov_b32_e32 v15, v93
	v_mov_b32_e32 v16, v94
	v_mov_b32_e32 v17, v95
	global_load_dword v119, v[54:55], off offset:480
	global_load_dwordx2 v[110:111], v[52:53], off
	v_lshl_add_u64 v[52:53], v[52:53], 0, s[98:99]
	global_load_dwordx4 v[92:95], v[48:49], off
	v_lshl_add_u64 v[48:49], v[48:49], 0, s[100:101]
	s_waitcnt lgkmcnt(0)
	v_mul_f32_e32 v27, v18, v26
	v_mul_f32_e32 v28, v19, v26
	v_mul_f32_e32 v20, v20, v26
	v_mul_f32_e32 v21, v21, v26
	s_nop 0
	v_lshlrev_b32_e32 v18, 16, v22
	v_mul_f32_e32 v26, 0xbfb8aa3b, v27
	v_and_b32_e32 v19, 0xffff0000, v22
	v_mul_f32_e32 v22, 0xbfb8aa3b, v28
	v_mul_f32_e32 v27, 0xbfb8aa3b, v20
	v_mul_f32_e32 v28, 0xbfb8aa3b, v21
	v_exp_f32_e32 v20, v26
	v_exp_f32_e32 v21, v22
	v_exp_f32_e32 v26, v27
	v_exp_f32_e32 v27, v28
	v_lshlrev_b32_e32 v22, 16, v23
	v_pk_add_f32 v[20:21], v[20:21], 1.0 op_sel_hi:[1,0]
	v_and_b32_e32 v23, 0xffff0000, v23
	v_div_scale_f32 v28, s[0:1], v21, v21, 1.0
	v_pk_add_f32 v[26:27], v[26:27], 1.0 op_sel_hi:[1,0]
	v_div_scale_f32 v30, s[0:1], v20, v20, 1.0
	v_rcp_f32_e32 v36, v28
	v_div_scale_f32 v32, s[6:7], v27, v27, 1.0
	v_rcp_f32_e32 v37, v30
	v_div_scale_f32 v34, s[8:9], v26, v26, 1.0
	v_rcp_f32_e32 v38, v32
	v_rcp_f32_e32 v39, v34
	v_fma_f32 v40, -v28, v36, 1.0
	v_div_scale_f32 v29, vcc, 1.0, v21, 1.0
	v_fma_f32 v41, -v30, v37, 1.0
	v_fmac_f32_e32 v36, v40, v36
	v_div_scale_f32 v31, s[0:1], 1.0, v20, 1.0
	v_fma_f32 v42, -v32, v38, 1.0
	v_fmac_f32_e32 v37, v41, v37
	v_mul_f32_e32 v40, v29, v36
	v_div_scale_f32 v33, s[6:7], 1.0, v27, 1.0
	v_fma_f32 v43, -v34, v39, 1.0
	v_fmac_f32_e32 v38, v42, v38
	v_mul_f32_e32 v41, v31, v37
	v_fma_f32 v44, -v28, v40, v29
	v_div_scale_f32 v35, s[8:9], 1.0, v26, 1.0
	v_fmac_f32_e32 v39, v43, v39
	v_mul_f32_e32 v42, v33, v38
	v_fma_f32 v45, -v30, v41, v31
	v_fmac_f32_e32 v40, v44, v36
	v_mul_f32_e32 v43, v35, v39
	v_fma_f32 v46, -v32, v42, v33
	v_fmac_f32_e32 v41, v45, v37
	v_fma_f32 v28, -v28, v40, v29
	v_fma_f32 v47, -v34, v43, v35
	v_fmac_f32_e32 v42, v46, v38
	v_fma_f32 v29, -v30, v41, v31
	v_div_fmas_f32 v28, v28, v36, v40
	s_mov_b64 vcc, s[0:1]
	v_fmac_f32_e32 v43, v47, v39
	v_fma_f32 v30, -v32, v42, v33
	v_div_fixup_f32 v21, v28, v21, 1.0
	v_div_fmas_f32 v28, v29, v37, v41
	s_mov_b64 vcc, s[6:7]
	v_fma_f32 v31, -v34, v43, v35
	v_div_fixup_f32 v20, v28, v20, 1.0
	v_div_fmas_f32 v28, v30, v38, v42
	s_mov_b64 vcc, s[8:9]
	s_nop 0
	v_pk_fma_f32 v[18:19], v[20:21], v[18:19], v[14:15]
	v_div_fmas_f32 v14, v31, v39, v43
	v_div_fixup_f32 v15, v28, v27, 1.0
	v_div_fixup_f32 v14, v14, v26, 1.0
	v_pk_mul_f32 v[26:27], v[18:19], v[18:19]
	v_pk_fma_f32 v[20:21], v[14:15], v[22:23], v[16:17]
	v_add_f32_e32 v16, v26, v27
	v_pk_mul_f32 v[14:15], v[20:21], v[20:21]
	global_store_dwordx4 v[50:51], v[18:21], off
	v_add_f32_e32 v14, v16, v14
	v_add_f32_e32 v14, v15, v14
	v_lshl_add_u64 v[50:51], v[50:51], 0, s[100:101]
	s_nop 0
	v_add_f32_dpp v15, v14, v14 quad_perm:[1,0,3,2] row_mask:0xf bank_mask:0xf
	s_nop 1
	v_add_f32_dpp v14, v15, v15 quad_perm:[2,3,0,1] row_mask:0xf bank_mask:0xf
	s_nop 1
	v_add_f32_dpp v15, v14, v14 row_half_mirror row_mask:0xf bank_mask:0xf
	s_nop 1
	v_add_f32_dpp v14, v15, v15 row_mirror row_mask:0xf bank_mask:0xf
	s_nop 1
	v_readlane_b32 s0, v14, 16
	v_readlane_b32 s1, v14, 48
	s_nop 1
	v_mov_b32_e32 v15, s0
	v_mov_b32_e32 v16, s1
	v_cndmask_b32_e64 v15, v15, v16, s[24:25]
	v_add_f32_e32 v14, v14, v15
	s_and_saveexec_b64 s[0:1], s[4:5]
	global_store_dword v[56:57], v14, off offset:224
	s_or_b64 exec, exec, s[0:1]
	ds_read_b128 v[18:21], v58 offset:32768
	s_waitcnt vmcnt(29)
	v_mov_b32_e32 v26, v112
	v_mov_b32_e32 v22, v96
	v_mov_b32_e32 v23, v97
	v_mov_b32_e32 v14, v64
	v_mov_b32_e32 v15, v65
	v_mov_b32_e32 v16, v66
	v_mov_b32_e32 v17, v67
	s_waitcnt lgkmcnt(0)
	v_mul_f32_e32 v27, v18, v26
	v_mul_f32_e32 v28, v19, v26
	v_mul_f32_e32 v20, v20, v26
	v_mul_f32_e32 v21, v21, v26
	s_nop 0
	v_lshlrev_b32_e32 v18, 16, v22
	v_mul_f32_e32 v26, 0xbfb8aa3b, v27
	v_and_b32_e32 v19, 0xffff0000, v22
	v_mul_f32_e32 v22, 0xbfb8aa3b, v28
	v_mul_f32_e32 v27, 0xbfb8aa3b, v20
	v_mul_f32_e32 v28, 0xbfb8aa3b, v21
	v_exp_f32_e32 v20, v26
	v_exp_f32_e32 v21, v22
	v_exp_f32_e32 v26, v27
	v_exp_f32_e32 v27, v28
	v_lshlrev_b32_e32 v22, 16, v23
	v_pk_add_f32 v[20:21], v[20:21], 1.0 op_sel_hi:[1,0]
	v_and_b32_e32 v23, 0xffff0000, v23
	v_div_scale_f32 v28, s[0:1], v21, v21, 1.0
	v_pk_add_f32 v[26:27], v[26:27], 1.0 op_sel_hi:[1,0]
	v_div_scale_f32 v30, s[0:1], v20, v20, 1.0
	v_rcp_f32_e32 v36, v28
	v_div_scale_f32 v32, s[6:7], v27, v27, 1.0
	v_rcp_f32_e32 v37, v30
	v_div_scale_f32 v34, s[8:9], v26, v26, 1.0
	v_rcp_f32_e32 v38, v32
	v_rcp_f32_e32 v39, v34
	v_fma_f32 v40, -v28, v36, 1.0
	v_div_scale_f32 v29, vcc, 1.0, v21, 1.0
	v_fma_f32 v41, -v30, v37, 1.0
	v_fmac_f32_e32 v36, v40, v36
	v_div_scale_f32 v31, s[0:1], 1.0, v20, 1.0
	v_fma_f32 v42, -v32, v38, 1.0
	v_fmac_f32_e32 v37, v41, v37
	v_mul_f32_e32 v40, v29, v36
	v_div_scale_f32 v33, s[6:7], 1.0, v27, 1.0
	v_fma_f32 v43, -v34, v39, 1.0
	v_fmac_f32_e32 v38, v42, v38
	v_mul_f32_e32 v41, v31, v37
	v_fma_f32 v44, -v28, v40, v29
	v_div_scale_f32 v35, s[8:9], 1.0, v26, 1.0
	v_fmac_f32_e32 v39, v43, v39
	v_mul_f32_e32 v42, v33, v38
	v_fma_f32 v45, -v30, v41, v31
	v_fmac_f32_e32 v40, v44, v36
	v_mul_f32_e32 v43, v35, v39
	v_fma_f32 v46, -v32, v42, v33
	v_fmac_f32_e32 v41, v45, v37
	v_fma_f32 v28, -v28, v40, v29
	v_fma_f32 v47, -v34, v43, v35
	v_fmac_f32_e32 v42, v46, v38
	v_fma_f32 v29, -v30, v41, v31
	v_div_fmas_f32 v28, v28, v36, v40
	s_mov_b64 vcc, s[0:1]
	v_fmac_f32_e32 v43, v47, v39
	v_fma_f32 v30, -v32, v42, v33
	v_div_fixup_f32 v21, v28, v21, 1.0
	v_div_fmas_f32 v28, v29, v37, v41
	s_mov_b64 vcc, s[6:7]
	v_fma_f32 v31, -v34, v43, v35
	v_div_fixup_f32 v20, v28, v20, 1.0
	v_div_fmas_f32 v28, v30, v38, v42
	s_mov_b64 vcc, s[8:9]
	s_nop 0
	v_pk_fma_f32 v[18:19], v[20:21], v[18:19], v[14:15]
	v_div_fmas_f32 v14, v31, v39, v43
	v_div_fixup_f32 v15, v28, v27, 1.0
	v_div_fixup_f32 v14, v14, v26, 1.0
	v_pk_mul_f32 v[26:27], v[18:19], v[18:19]
	v_pk_fma_f32 v[20:21], v[14:15], v[22:23], v[16:17]
	v_add_f32_e32 v16, v26, v27
	v_pk_mul_f32 v[14:15], v[20:21], v[20:21]
	global_store_dwordx4 v[50:51], v[18:21], off
	v_add_f32_e32 v14, v16, v14
	v_add_f32_e32 v14, v15, v14
	v_lshl_add_u64 v[50:51], v[50:51], 0, s[100:101]
	s_nop 0
	v_add_f32_dpp v15, v14, v14 quad_perm:[1,0,3,2] row_mask:0xf bank_mask:0xf
	s_nop 1
	v_add_f32_dpp v14, v15, v15 quad_perm:[2,3,0,1] row_mask:0xf bank_mask:0xf
	s_nop 1
	v_add_f32_dpp v15, v14, v14 row_half_mirror row_mask:0xf bank_mask:0xf
	s_nop 1
	v_add_f32_dpp v14, v15, v15 row_mirror row_mask:0xf bank_mask:0xf
	s_nop 1
	v_readlane_b32 s0, v14, 16
	v_readlane_b32 s1, v14, 48
	s_nop 1
	v_mov_b32_e32 v15, s0
	v_mov_b32_e32 v16, s1
	v_cndmask_b32_e64 v15, v15, v16, s[24:25]
	v_add_f32_e32 v14, v14, v15
	s_and_saveexec_b64 s[0:1], s[4:5]
	global_store_dword v[56:57], v14, off offset:256
	s_or_b64 exec, exec, s[0:1]
	ds_read_b128 v[18:21], v58 offset:36864
	s_waitcnt vmcnt(26)
	v_mov_b32_e32 v26, v113
	v_mov_b32_e32 v22, v98
	v_mov_b32_e32 v23, v99
	v_mov_b32_e32 v14, v68
	v_mov_b32_e32 v15, v69
	v_mov_b32_e32 v16, v70
	v_mov_b32_e32 v17, v71
	s_waitcnt lgkmcnt(0)
	v_mul_f32_e32 v27, v18, v26
	v_mul_f32_e32 v28, v19, v26
	v_mul_f32_e32 v20, v20, v26
	v_mul_f32_e32 v21, v21, v26
	s_nop 0
	v_lshlrev_b32_e32 v18, 16, v22
	v_mul_f32_e32 v26, 0xbfb8aa3b, v27
	v_and_b32_e32 v19, 0xffff0000, v22
	v_mul_f32_e32 v22, 0xbfb8aa3b, v28
	v_mul_f32_e32 v27, 0xbfb8aa3b, v20
	v_mul_f32_e32 v28, 0xbfb8aa3b, v21
	v_exp_f32_e32 v20, v26
	v_exp_f32_e32 v21, v22
	v_exp_f32_e32 v26, v27
	v_exp_f32_e32 v27, v28
	v_lshlrev_b32_e32 v22, 16, v23
	v_pk_add_f32 v[20:21], v[20:21], 1.0 op_sel_hi:[1,0]
	v_and_b32_e32 v23, 0xffff0000, v23
	v_div_scale_f32 v28, s[0:1], v21, v21, 1.0
	v_pk_add_f32 v[26:27], v[26:27], 1.0 op_sel_hi:[1,0]
	v_div_scale_f32 v30, s[0:1], v20, v20, 1.0
	v_rcp_f32_e32 v36, v28
	v_div_scale_f32 v32, s[6:7], v27, v27, 1.0
	v_rcp_f32_e32 v37, v30
	v_div_scale_f32 v34, s[8:9], v26, v26, 1.0
	v_rcp_f32_e32 v38, v32
	v_rcp_f32_e32 v39, v34
	v_fma_f32 v40, -v28, v36, 1.0
	v_div_scale_f32 v29, vcc, 1.0, v21, 1.0
	v_fma_f32 v41, -v30, v37, 1.0
	v_fmac_f32_e32 v36, v40, v36
	v_div_scale_f32 v31, s[0:1], 1.0, v20, 1.0
	v_fma_f32 v42, -v32, v38, 1.0
	v_fmac_f32_e32 v37, v41, v37
	v_mul_f32_e32 v40, v29, v36
	v_div_scale_f32 v33, s[6:7], 1.0, v27, 1.0
	v_fma_f32 v43, -v34, v39, 1.0
	v_fmac_f32_e32 v38, v42, v38
	v_mul_f32_e32 v41, v31, v37
	v_fma_f32 v44, -v28, v40, v29
	v_div_scale_f32 v35, s[8:9], 1.0, v26, 1.0
	v_fmac_f32_e32 v39, v43, v39
	v_mul_f32_e32 v42, v33, v38
	v_fma_f32 v45, -v30, v41, v31
	v_fmac_f32_e32 v40, v44, v36
	v_mul_f32_e32 v43, v35, v39
	v_fma_f32 v46, -v32, v42, v33
	v_fmac_f32_e32 v41, v45, v37
	v_fma_f32 v28, -v28, v40, v29
	v_fma_f32 v47, -v34, v43, v35
	v_fmac_f32_e32 v42, v46, v38
	v_fma_f32 v29, -v30, v41, v31
	v_div_fmas_f32 v28, v28, v36, v40
	s_mov_b64 vcc, s[0:1]
	v_fmac_f32_e32 v43, v47, v39
	v_fma_f32 v30, -v32, v42, v33
	v_div_fixup_f32 v21, v28, v21, 1.0
	v_div_fmas_f32 v28, v29, v37, v41
	s_mov_b64 vcc, s[6:7]
	v_fma_f32 v31, -v34, v43, v35
	v_div_fixup_f32 v20, v28, v20, 1.0
	v_div_fmas_f32 v28, v30, v38, v42
	s_mov_b64 vcc, s[8:9]
	s_nop 0
	v_pk_fma_f32 v[18:19], v[20:21], v[18:19], v[14:15]
	v_div_fmas_f32 v14, v31, v39, v43
	v_div_fixup_f32 v15, v28, v27, 1.0
	v_div_fixup_f32 v14, v14, v26, 1.0
	v_pk_mul_f32 v[26:27], v[18:19], v[18:19]
	v_pk_fma_f32 v[20:21], v[14:15], v[22:23], v[16:17]
	v_add_f32_e32 v16, v26, v27
	v_pk_mul_f32 v[14:15], v[20:21], v[20:21]
	global_store_dwordx4 v[50:51], v[18:21], off
	v_add_f32_e32 v14, v16, v14
	v_add_f32_e32 v14, v15, v14
	v_lshl_add_u64 v[50:51], v[50:51], 0, s[100:101]
	s_nop 0
	v_add_f32_dpp v15, v14, v14 quad_perm:[1,0,3,2] row_mask:0xf bank_mask:0xf
	s_nop 1
	v_add_f32_dpp v14, v15, v15 quad_perm:[2,3,0,1] row_mask:0xf bank_mask:0xf
	s_nop 1
	v_add_f32_dpp v15, v14, v14 row_half_mirror row_mask:0xf bank_mask:0xf
	s_nop 1
	v_add_f32_dpp v14, v15, v15 row_mirror row_mask:0xf bank_mask:0xf
	s_nop 1
	v_readlane_b32 s0, v14, 16
	v_readlane_b32 s1, v14, 48
	s_nop 1
	v_mov_b32_e32 v15, s0
	v_mov_b32_e32 v16, s1
	v_cndmask_b32_e64 v15, v15, v16, s[24:25]
	v_add_f32_e32 v14, v14, v15
	s_and_saveexec_b64 s[0:1], s[4:5]
	global_store_dword v[56:57], v14, off offset:288
	s_or_b64 exec, exec, s[0:1]
	ds_read_b128 v[18:21], v58 offset:40960
	s_waitcnt vmcnt(23)
	v_mov_b32_e32 v26, v114
	v_mov_b32_e32 v22, v100
	v_mov_b32_e32 v23, v101
	v_mov_b32_e32 v14, v72
	v_mov_b32_e32 v15, v73
	v_mov_b32_e32 v16, v74
	v_mov_b32_e32 v17, v75
	s_waitcnt lgkmcnt(0)
	v_mul_f32_e32 v27, v18, v26
	v_mul_f32_e32 v28, v19, v26
	v_mul_f32_e32 v20, v20, v26
	v_mul_f32_e32 v21, v21, v26
	s_nop 0
	v_lshlrev_b32_e32 v18, 16, v22
	v_mul_f32_e32 v26, 0xbfb8aa3b, v27
	v_and_b32_e32 v19, 0xffff0000, v22
	v_mul_f32_e32 v22, 0xbfb8aa3b, v28
	v_mul_f32_e32 v27, 0xbfb8aa3b, v20
	v_mul_f32_e32 v28, 0xbfb8aa3b, v21
	v_exp_f32_e32 v20, v26
	v_exp_f32_e32 v21, v22
	v_exp_f32_e32 v26, v27
	v_exp_f32_e32 v27, v28
	v_lshlrev_b32_e32 v22, 16, v23
	v_pk_add_f32 v[20:21], v[20:21], 1.0 op_sel_hi:[1,0]
	v_and_b32_e32 v23, 0xffff0000, v23
	v_div_scale_f32 v28, s[0:1], v21, v21, 1.0
	v_pk_add_f32 v[26:27], v[26:27], 1.0 op_sel_hi:[1,0]
	v_div_scale_f32 v30, s[0:1], v20, v20, 1.0
	v_rcp_f32_e32 v36, v28
	v_div_scale_f32 v32, s[6:7], v27, v27, 1.0
	v_rcp_f32_e32 v37, v30
	v_div_scale_f32 v34, s[8:9], v26, v26, 1.0
	v_rcp_f32_e32 v38, v32
	v_rcp_f32_e32 v39, v34
	v_fma_f32 v40, -v28, v36, 1.0
	v_div_scale_f32 v29, vcc, 1.0, v21, 1.0
	v_fma_f32 v41, -v30, v37, 1.0
	v_fmac_f32_e32 v36, v40, v36
	v_div_scale_f32 v31, s[0:1], 1.0, v20, 1.0
	v_fma_f32 v42, -v32, v38, 1.0
	v_fmac_f32_e32 v37, v41, v37
	v_mul_f32_e32 v40, v29, v36
	v_div_scale_f32 v33, s[6:7], 1.0, v27, 1.0
	v_fma_f32 v43, -v34, v39, 1.0
	v_fmac_f32_e32 v38, v42, v38
	v_mul_f32_e32 v41, v31, v37
	v_fma_f32 v44, -v28, v40, v29
	v_div_scale_f32 v35, s[8:9], 1.0, v26, 1.0
	v_fmac_f32_e32 v39, v43, v39
	v_mul_f32_e32 v42, v33, v38
	v_fma_f32 v45, -v30, v41, v31
	v_fmac_f32_e32 v40, v44, v36
	v_mul_f32_e32 v43, v35, v39
	v_fma_f32 v46, -v32, v42, v33
	v_fmac_f32_e32 v41, v45, v37
	v_fma_f32 v28, -v28, v40, v29
	v_fma_f32 v47, -v34, v43, v35
	v_fmac_f32_e32 v42, v46, v38
	v_fma_f32 v29, -v30, v41, v31
	v_div_fmas_f32 v28, v28, v36, v40
	s_mov_b64 vcc, s[0:1]
	v_fmac_f32_e32 v43, v47, v39
	v_fma_f32 v30, -v32, v42, v33
	v_div_fixup_f32 v21, v28, v21, 1.0
	v_div_fmas_f32 v28, v29, v37, v41
	s_mov_b64 vcc, s[6:7]
	v_fma_f32 v31, -v34, v43, v35
	v_div_fixup_f32 v20, v28, v20, 1.0
	v_div_fmas_f32 v28, v30, v38, v42
	s_mov_b64 vcc, s[8:9]
	s_nop 0
	v_pk_fma_f32 v[18:19], v[20:21], v[18:19], v[14:15]
	v_div_fmas_f32 v14, v31, v39, v43
	v_div_fixup_f32 v15, v28, v27, 1.0
	v_div_fixup_f32 v14, v14, v26, 1.0
	v_pk_mul_f32 v[26:27], v[18:19], v[18:19]
	v_pk_fma_f32 v[20:21], v[14:15], v[22:23], v[16:17]
	v_add_f32_e32 v16, v26, v27
	v_pk_mul_f32 v[14:15], v[20:21], v[20:21]
	global_store_dwordx4 v[50:51], v[18:21], off
	v_add_f32_e32 v14, v16, v14
	v_add_f32_e32 v14, v15, v14
	v_lshl_add_u64 v[50:51], v[50:51], 0, s[100:101]
	s_nop 0
	v_add_f32_dpp v15, v14, v14 quad_perm:[1,0,3,2] row_mask:0xf bank_mask:0xf
	s_nop 1
	v_add_f32_dpp v14, v15, v15 quad_perm:[2,3,0,1] row_mask:0xf bank_mask:0xf
	s_nop 1
	v_add_f32_dpp v15, v14, v14 row_half_mirror row_mask:0xf bank_mask:0xf
	s_nop 1
	v_add_f32_dpp v14, v15, v15 row_mirror row_mask:0xf bank_mask:0xf
	s_nop 1
	v_readlane_b32 s0, v14, 16
	v_readlane_b32 s1, v14, 48
	s_nop 1
	v_mov_b32_e32 v15, s0
	v_mov_b32_e32 v16, s1
	v_cndmask_b32_e64 v15, v15, v16, s[24:25]
	v_add_f32_e32 v14, v14, v15
	s_and_saveexec_b64 s[0:1], s[4:5]
	global_store_dword v[56:57], v14, off offset:320
	s_or_b64 exec, exec, s[0:1]
	ds_read_b128 v[18:21], v58 offset:45056
	s_waitcnt vmcnt(20)
	v_mov_b32_e32 v26, v115
	v_mov_b32_e32 v22, v102
	v_mov_b32_e32 v23, v103
	v_mov_b32_e32 v14, v76
	v_mov_b32_e32 v15, v77
	v_mov_b32_e32 v16, v78
	v_mov_b32_e32 v17, v79
	s_waitcnt lgkmcnt(0)
	v_mul_f32_e32 v27, v18, v26
	v_mul_f32_e32 v28, v19, v26
	v_mul_f32_e32 v20, v20, v26
	v_mul_f32_e32 v21, v21, v26
	s_nop 0
	v_lshlrev_b32_e32 v18, 16, v22
	v_mul_f32_e32 v26, 0xbfb8aa3b, v27
	v_and_b32_e32 v19, 0xffff0000, v22
	v_mul_f32_e32 v22, 0xbfb8aa3b, v28
	v_mul_f32_e32 v27, 0xbfb8aa3b, v20
	v_mul_f32_e32 v28, 0xbfb8aa3b, v21
	v_exp_f32_e32 v20, v26
	v_exp_f32_e32 v21, v22
	v_exp_f32_e32 v26, v27
	v_exp_f32_e32 v27, v28
	v_lshlrev_b32_e32 v22, 16, v23
	v_pk_add_f32 v[20:21], v[20:21], 1.0 op_sel_hi:[1,0]
	v_and_b32_e32 v23, 0xffff0000, v23
	v_div_scale_f32 v28, s[0:1], v21, v21, 1.0
	v_pk_add_f32 v[26:27], v[26:27], 1.0 op_sel_hi:[1,0]
	v_div_scale_f32 v30, s[0:1], v20, v20, 1.0
	v_rcp_f32_e32 v36, v28
	v_div_scale_f32 v32, s[6:7], v27, v27, 1.0
	v_rcp_f32_e32 v37, v30
	v_div_scale_f32 v34, s[8:9], v26, v26, 1.0
	v_rcp_f32_e32 v38, v32
	v_rcp_f32_e32 v39, v34
	v_fma_f32 v40, -v28, v36, 1.0
	v_div_scale_f32 v29, vcc, 1.0, v21, 1.0
	v_fma_f32 v41, -v30, v37, 1.0
	v_fmac_f32_e32 v36, v40, v36
	v_div_scale_f32 v31, s[0:1], 1.0, v20, 1.0
	v_fma_f32 v42, -v32, v38, 1.0
	v_fmac_f32_e32 v37, v41, v37
	v_mul_f32_e32 v40, v29, v36
	v_div_scale_f32 v33, s[6:7], 1.0, v27, 1.0
	v_fma_f32 v43, -v34, v39, 1.0
	v_fmac_f32_e32 v38, v42, v38
	v_mul_f32_e32 v41, v31, v37
	v_fma_f32 v44, -v28, v40, v29
	v_div_scale_f32 v35, s[8:9], 1.0, v26, 1.0
	v_fmac_f32_e32 v39, v43, v39
	v_mul_f32_e32 v42, v33, v38
	v_fma_f32 v45, -v30, v41, v31
	v_fmac_f32_e32 v40, v44, v36
	v_mul_f32_e32 v43, v35, v39
	v_fma_f32 v46, -v32, v42, v33
	v_fmac_f32_e32 v41, v45, v37
	v_fma_f32 v28, -v28, v40, v29
	v_fma_f32 v47, -v34, v43, v35
	v_fmac_f32_e32 v42, v46, v38
	v_fma_f32 v29, -v30, v41, v31
	v_div_fmas_f32 v28, v28, v36, v40
	s_mov_b64 vcc, s[0:1]
	v_fmac_f32_e32 v43, v47, v39
	v_fma_f32 v30, -v32, v42, v33
	v_div_fixup_f32 v21, v28, v21, 1.0
	v_div_fmas_f32 v28, v29, v37, v41
	s_mov_b64 vcc, s[6:7]
	v_fma_f32 v31, -v34, v43, v35
	v_div_fixup_f32 v20, v28, v20, 1.0
	v_div_fmas_f32 v28, v30, v38, v42
	s_mov_b64 vcc, s[8:9]
	s_nop 0
	v_pk_fma_f32 v[18:19], v[20:21], v[18:19], v[14:15]
	v_div_fmas_f32 v14, v31, v39, v43
	v_div_fixup_f32 v15, v28, v27, 1.0
	v_div_fixup_f32 v14, v14, v26, 1.0
	v_pk_mul_f32 v[26:27], v[18:19], v[18:19]
	v_pk_fma_f32 v[20:21], v[14:15], v[22:23], v[16:17]
	v_add_f32_e32 v16, v26, v27
	v_pk_mul_f32 v[14:15], v[20:21], v[20:21]
	global_store_dwordx4 v[50:51], v[18:21], off
	v_add_f32_e32 v14, v16, v14
	v_add_f32_e32 v14, v15, v14
	v_lshl_add_u64 v[50:51], v[50:51], 0, s[100:101]
	s_nop 0
	v_add_f32_dpp v15, v14, v14 quad_perm:[1,0,3,2] row_mask:0xf bank_mask:0xf
	s_nop 1
	v_add_f32_dpp v14, v15, v15 quad_perm:[2,3,0,1] row_mask:0xf bank_mask:0xf
	s_nop 1
	v_add_f32_dpp v15, v14, v14 row_half_mirror row_mask:0xf bank_mask:0xf
	s_nop 1
	v_add_f32_dpp v14, v15, v15 row_mirror row_mask:0xf bank_mask:0xf
	s_nop 1
	v_readlane_b32 s0, v14, 16
	v_readlane_b32 s1, v14, 48
	s_nop 1
	v_mov_b32_e32 v15, s0
	v_mov_b32_e32 v16, s1
	v_cndmask_b32_e64 v15, v15, v16, s[24:25]
	v_add_f32_e32 v14, v14, v15
	s_and_saveexec_b64 s[0:1], s[4:5]
	global_store_dword v[56:57], v14, off offset:352
	s_or_b64 exec, exec, s[0:1]
	ds_read_b128 v[18:21], v58 offset:49152
	s_waitcnt vmcnt(17)
	v_mov_b32_e32 v26, v116
	v_mov_b32_e32 v22, v104
	v_mov_b32_e32 v23, v105
	v_mov_b32_e32 v14, v80
	v_mov_b32_e32 v15, v81
	v_mov_b32_e32 v16, v82
	v_mov_b32_e32 v17, v83
	s_waitcnt lgkmcnt(0)
	v_mul_f32_e32 v27, v18, v26
	v_mul_f32_e32 v28, v19, v26
	v_mul_f32_e32 v20, v20, v26
	v_mul_f32_e32 v21, v21, v26
	s_nop 0
	v_lshlrev_b32_e32 v18, 16, v22
	v_mul_f32_e32 v26, 0xbfb8aa3b, v27
	v_and_b32_e32 v19, 0xffff0000, v22
	v_mul_f32_e32 v22, 0xbfb8aa3b, v28
	v_mul_f32_e32 v27, 0xbfb8aa3b, v20
	v_mul_f32_e32 v28, 0xbfb8aa3b, v21
	v_exp_f32_e32 v20, v26
	v_exp_f32_e32 v21, v22
	v_exp_f32_e32 v26, v27
	v_exp_f32_e32 v27, v28
	v_lshlrev_b32_e32 v22, 16, v23
	v_pk_add_f32 v[20:21], v[20:21], 1.0 op_sel_hi:[1,0]
	v_and_b32_e32 v23, 0xffff0000, v23
	v_div_scale_f32 v28, s[0:1], v21, v21, 1.0
	v_pk_add_f32 v[26:27], v[26:27], 1.0 op_sel_hi:[1,0]
	v_div_scale_f32 v30, s[0:1], v20, v20, 1.0
	v_rcp_f32_e32 v36, v28
	v_div_scale_f32 v32, s[6:7], v27, v27, 1.0
	v_rcp_f32_e32 v37, v30
	v_div_scale_f32 v34, s[8:9], v26, v26, 1.0
	v_rcp_f32_e32 v38, v32
	v_rcp_f32_e32 v39, v34
	v_fma_f32 v40, -v28, v36, 1.0
	v_div_scale_f32 v29, vcc, 1.0, v21, 1.0
	v_fma_f32 v41, -v30, v37, 1.0
	v_fmac_f32_e32 v36, v40, v36
	v_div_scale_f32 v31, s[0:1], 1.0, v20, 1.0
	v_fma_f32 v42, -v32, v38, 1.0
	v_fmac_f32_e32 v37, v41, v37
	v_mul_f32_e32 v40, v29, v36
	v_div_scale_f32 v33, s[6:7], 1.0, v27, 1.0
	v_fma_f32 v43, -v34, v39, 1.0
	v_fmac_f32_e32 v38, v42, v38
	v_mul_f32_e32 v41, v31, v37
	v_fma_f32 v44, -v28, v40, v29
	v_div_scale_f32 v35, s[8:9], 1.0, v26, 1.0
	v_fmac_f32_e32 v39, v43, v39
	v_mul_f32_e32 v42, v33, v38
	v_fma_f32 v45, -v30, v41, v31
	v_fmac_f32_e32 v40, v44, v36
	v_mul_f32_e32 v43, v35, v39
	v_fma_f32 v46, -v32, v42, v33
	v_fmac_f32_e32 v41, v45, v37
	v_fma_f32 v28, -v28, v40, v29
	v_fma_f32 v47, -v34, v43, v35
	v_fmac_f32_e32 v42, v46, v38
	v_fma_f32 v29, -v30, v41, v31
	v_div_fmas_f32 v28, v28, v36, v40
	s_mov_b64 vcc, s[0:1]
	v_fmac_f32_e32 v43, v47, v39
	v_fma_f32 v30, -v32, v42, v33
	v_div_fixup_f32 v21, v28, v21, 1.0
	v_div_fmas_f32 v28, v29, v37, v41
	s_mov_b64 vcc, s[6:7]
	v_fma_f32 v31, -v34, v43, v35
	v_div_fixup_f32 v20, v28, v20, 1.0
	v_div_fmas_f32 v28, v30, v38, v42
	s_mov_b64 vcc, s[8:9]
	s_nop 0
	v_pk_fma_f32 v[18:19], v[20:21], v[18:19], v[14:15]
	v_div_fmas_f32 v14, v31, v39, v43
	v_div_fixup_f32 v15, v28, v27, 1.0
	v_div_fixup_f32 v14, v14, v26, 1.0
	v_pk_mul_f32 v[26:27], v[18:19], v[18:19]
	v_pk_fma_f32 v[20:21], v[14:15], v[22:23], v[16:17]
	v_add_f32_e32 v16, v26, v27
	v_pk_mul_f32 v[14:15], v[20:21], v[20:21]
	global_store_dwordx4 v[50:51], v[18:21], off
	v_add_f32_e32 v14, v16, v14
	v_add_f32_e32 v14, v15, v14
	v_lshl_add_u64 v[50:51], v[50:51], 0, s[100:101]
	s_nop 0
	v_add_f32_dpp v15, v14, v14 quad_perm:[1,0,3,2] row_mask:0xf bank_mask:0xf
	s_nop 1
	v_add_f32_dpp v14, v15, v15 quad_perm:[2,3,0,1] row_mask:0xf bank_mask:0xf
	s_nop 1
	v_add_f32_dpp v15, v14, v14 row_half_mirror row_mask:0xf bank_mask:0xf
	s_nop 1
	v_add_f32_dpp v14, v15, v15 row_mirror row_mask:0xf bank_mask:0xf
	s_nop 1
	v_readlane_b32 s0, v14, 16
	v_readlane_b32 s1, v14, 48
	s_nop 1
	v_mov_b32_e32 v15, s0
	v_mov_b32_e32 v16, s1
	v_cndmask_b32_e64 v15, v15, v16, s[24:25]
	v_add_f32_e32 v14, v14, v15
	s_and_saveexec_b64 s[0:1], s[4:5]
	global_store_dword v[56:57], v14, off offset:384
	s_or_b64 exec, exec, s[0:1]
	ds_read_b128 v[18:21], v58 offset:53248
	s_waitcnt vmcnt(14)
	v_mov_b32_e32 v26, v117
	v_mov_b32_e32 v22, v106
	v_mov_b32_e32 v23, v107
	v_mov_b32_e32 v14, v84
	v_mov_b32_e32 v15, v85
	v_mov_b32_e32 v16, v86
	v_mov_b32_e32 v17, v87
	s_waitcnt lgkmcnt(0)
	v_mul_f32_e32 v27, v18, v26
	v_mul_f32_e32 v28, v19, v26
	v_mul_f32_e32 v20, v20, v26
	v_mul_f32_e32 v21, v21, v26
	s_nop 0
	v_lshlrev_b32_e32 v18, 16, v22
	v_mul_f32_e32 v26, 0xbfb8aa3b, v27
	v_and_b32_e32 v19, 0xffff0000, v22
	v_mul_f32_e32 v22, 0xbfb8aa3b, v28
	v_mul_f32_e32 v27, 0xbfb8aa3b, v20
	v_mul_f32_e32 v28, 0xbfb8aa3b, v21
	v_exp_f32_e32 v20, v26
	v_exp_f32_e32 v21, v22
	v_exp_f32_e32 v26, v27
	v_exp_f32_e32 v27, v28
	v_lshlrev_b32_e32 v22, 16, v23
	v_pk_add_f32 v[20:21], v[20:21], 1.0 op_sel_hi:[1,0]
	v_and_b32_e32 v23, 0xffff0000, v23
	v_div_scale_f32 v28, s[0:1], v21, v21, 1.0
	v_pk_add_f32 v[26:27], v[26:27], 1.0 op_sel_hi:[1,0]
	v_div_scale_f32 v30, s[0:1], v20, v20, 1.0
	v_rcp_f32_e32 v36, v28
	v_div_scale_f32 v32, s[6:7], v27, v27, 1.0
	v_rcp_f32_e32 v37, v30
	v_div_scale_f32 v34, s[8:9], v26, v26, 1.0
	v_rcp_f32_e32 v38, v32
	v_rcp_f32_e32 v39, v34
	v_fma_f32 v40, -v28, v36, 1.0
	v_div_scale_f32 v29, vcc, 1.0, v21, 1.0
	v_fma_f32 v41, -v30, v37, 1.0
	v_fmac_f32_e32 v36, v40, v36
	v_div_scale_f32 v31, s[0:1], 1.0, v20, 1.0
	v_fma_f32 v42, -v32, v38, 1.0
	v_fmac_f32_e32 v37, v41, v37
	v_mul_f32_e32 v40, v29, v36
	v_div_scale_f32 v33, s[6:7], 1.0, v27, 1.0
	v_fma_f32 v43, -v34, v39, 1.0
	v_fmac_f32_e32 v38, v42, v38
	v_mul_f32_e32 v41, v31, v37
	v_fma_f32 v44, -v28, v40, v29
	v_div_scale_f32 v35, s[8:9], 1.0, v26, 1.0
	v_fmac_f32_e32 v39, v43, v39
	v_mul_f32_e32 v42, v33, v38
	v_fma_f32 v45, -v30, v41, v31
	v_fmac_f32_e32 v40, v44, v36
	v_mul_f32_e32 v43, v35, v39
	v_fma_f32 v46, -v32, v42, v33
	v_fmac_f32_e32 v41, v45, v37
	v_fma_f32 v28, -v28, v40, v29
	v_fma_f32 v47, -v34, v43, v35
	v_fmac_f32_e32 v42, v46, v38
	v_fma_f32 v29, -v30, v41, v31
	v_div_fmas_f32 v28, v28, v36, v40
	s_mov_b64 vcc, s[0:1]
	v_fmac_f32_e32 v43, v47, v39
	v_fma_f32 v30, -v32, v42, v33
	v_div_fixup_f32 v21, v28, v21, 1.0
	v_div_fmas_f32 v28, v29, v37, v41
	s_mov_b64 vcc, s[6:7]
	v_fma_f32 v31, -v34, v43, v35
	v_div_fixup_f32 v20, v28, v20, 1.0
	v_div_fmas_f32 v28, v30, v38, v42
	s_mov_b64 vcc, s[8:9]
	s_nop 0
	v_pk_fma_f32 v[18:19], v[20:21], v[18:19], v[14:15]
	v_div_fmas_f32 v14, v31, v39, v43
	v_div_fixup_f32 v15, v28, v27, 1.0
	v_div_fixup_f32 v14, v14, v26, 1.0
	v_pk_mul_f32 v[26:27], v[18:19], v[18:19]
	v_pk_fma_f32 v[20:21], v[14:15], v[22:23], v[16:17]
	v_add_f32_e32 v16, v26, v27
	v_pk_mul_f32 v[14:15], v[20:21], v[20:21]
	global_store_dwordx4 v[50:51], v[18:21], off
	v_add_f32_e32 v14, v16, v14
	v_add_f32_e32 v14, v15, v14
	v_lshl_add_u64 v[50:51], v[50:51], 0, s[100:101]
	s_nop 0
	v_add_f32_dpp v15, v14, v14 quad_perm:[1,0,3,2] row_mask:0xf bank_mask:0xf
	s_nop 1
	v_add_f32_dpp v14, v15, v15 quad_perm:[2,3,0,1] row_mask:0xf bank_mask:0xf
	s_nop 1
	v_add_f32_dpp v15, v14, v14 row_half_mirror row_mask:0xf bank_mask:0xf
	s_nop 1
	v_add_f32_dpp v14, v15, v15 row_mirror row_mask:0xf bank_mask:0xf
	s_nop 1
	v_readlane_b32 s0, v14, 16
	v_readlane_b32 s1, v14, 48
	s_nop 1
	v_mov_b32_e32 v15, s0
	v_mov_b32_e32 v16, s1
	v_cndmask_b32_e64 v15, v15, v16, s[24:25]
	v_add_f32_e32 v14, v14, v15
	s_and_saveexec_b64 s[0:1], s[4:5]
	global_store_dword v[56:57], v14, off offset:416
	s_or_b64 exec, exec, s[0:1]
	ds_read_b128 v[18:21], v58 offset:57344
	s_waitcnt vmcnt(11)
	v_mov_b32_e32 v26, v118
	v_mov_b32_e32 v22, v108
	v_mov_b32_e32 v23, v109
	v_mov_b32_e32 v14, v88
	v_mov_b32_e32 v15, v89
	v_mov_b32_e32 v16, v90
	v_mov_b32_e32 v17, v91
	s_waitcnt lgkmcnt(0)
	v_mul_f32_e32 v27, v18, v26
	v_mul_f32_e32 v28, v19, v26
	v_mul_f32_e32 v20, v20, v26
	v_mul_f32_e32 v21, v21, v26
	s_nop 0
	v_lshlrev_b32_e32 v18, 16, v22
	v_mul_f32_e32 v26, 0xbfb8aa3b, v27
	v_and_b32_e32 v19, 0xffff0000, v22
	v_mul_f32_e32 v22, 0xbfb8aa3b, v28
	v_mul_f32_e32 v27, 0xbfb8aa3b, v20
	v_mul_f32_e32 v28, 0xbfb8aa3b, v21
	v_exp_f32_e32 v20, v26
	v_exp_f32_e32 v21, v22
	v_exp_f32_e32 v26, v27
	v_exp_f32_e32 v27, v28
	v_lshlrev_b32_e32 v22, 16, v23
	v_pk_add_f32 v[20:21], v[20:21], 1.0 op_sel_hi:[1,0]
	v_and_b32_e32 v23, 0xffff0000, v23
	v_div_scale_f32 v28, s[0:1], v21, v21, 1.0
	v_pk_add_f32 v[26:27], v[26:27], 1.0 op_sel_hi:[1,0]
	v_div_scale_f32 v30, s[0:1], v20, v20, 1.0
	v_rcp_f32_e32 v36, v28
	v_div_scale_f32 v32, s[6:7], v27, v27, 1.0
	v_rcp_f32_e32 v37, v30
	v_div_scale_f32 v34, s[8:9], v26, v26, 1.0
	v_rcp_f32_e32 v38, v32
	v_rcp_f32_e32 v39, v34
	v_fma_f32 v40, -v28, v36, 1.0
	v_div_scale_f32 v29, vcc, 1.0, v21, 1.0
	v_fma_f32 v41, -v30, v37, 1.0
	v_fmac_f32_e32 v36, v40, v36
	v_div_scale_f32 v31, s[0:1], 1.0, v20, 1.0
	v_fma_f32 v42, -v32, v38, 1.0
	v_fmac_f32_e32 v37, v41, v37
	v_mul_f32_e32 v40, v29, v36
	v_div_scale_f32 v33, s[6:7], 1.0, v27, 1.0
	v_fma_f32 v43, -v34, v39, 1.0
	v_fmac_f32_e32 v38, v42, v38
	v_mul_f32_e32 v41, v31, v37
	v_fma_f32 v44, -v28, v40, v29
	v_div_scale_f32 v35, s[8:9], 1.0, v26, 1.0
	v_fmac_f32_e32 v39, v43, v39
	v_mul_f32_e32 v42, v33, v38
	v_fma_f32 v45, -v30, v41, v31
	v_fmac_f32_e32 v40, v44, v36
	v_mul_f32_e32 v43, v35, v39
	v_fma_f32 v46, -v32, v42, v33
	v_fmac_f32_e32 v41, v45, v37
	v_fma_f32 v28, -v28, v40, v29
	v_fma_f32 v47, -v34, v43, v35
	v_fmac_f32_e32 v42, v46, v38
	v_fma_f32 v29, -v30, v41, v31
	v_div_fmas_f32 v28, v28, v36, v40
	s_mov_b64 vcc, s[0:1]
	v_fmac_f32_e32 v43, v47, v39
	v_fma_f32 v30, -v32, v42, v33
	v_div_fixup_f32 v21, v28, v21, 1.0
	v_div_fmas_f32 v28, v29, v37, v41
	s_mov_b64 vcc, s[6:7]
	v_fma_f32 v31, -v34, v43, v35
	v_div_fixup_f32 v20, v28, v20, 1.0
	v_div_fmas_f32 v28, v30, v38, v42
	s_mov_b64 vcc, s[8:9]
	s_nop 0
	v_pk_fma_f32 v[18:19], v[20:21], v[18:19], v[14:15]
	v_div_fmas_f32 v14, v31, v39, v43
	v_div_fixup_f32 v15, v28, v27, 1.0
	v_div_fixup_f32 v14, v14, v26, 1.0
	v_pk_mul_f32 v[26:27], v[18:19], v[18:19]
	v_pk_fma_f32 v[20:21], v[14:15], v[22:23], v[16:17]
	v_add_f32_e32 v16, v26, v27
	v_pk_mul_f32 v[14:15], v[20:21], v[20:21]
	global_store_dwordx4 v[50:51], v[18:21], off
	v_add_f32_e32 v14, v16, v14
	v_add_f32_e32 v14, v15, v14
	v_lshl_add_u64 v[50:51], v[50:51], 0, s[100:101]
	s_nop 0
	v_add_f32_dpp v15, v14, v14 quad_perm:[1,0,3,2] row_mask:0xf bank_mask:0xf
	s_nop 1
	v_add_f32_dpp v14, v15, v15 quad_perm:[2,3,0,1] row_mask:0xf bank_mask:0xf
	s_nop 1
	v_add_f32_dpp v15, v14, v14 row_half_mirror row_mask:0xf bank_mask:0xf
	s_nop 1
	v_add_f32_dpp v14, v15, v15 row_mirror row_mask:0xf bank_mask:0xf
	s_nop 1
	v_readlane_b32 s0, v14, 16
	v_readlane_b32 s1, v14, 48
	s_nop 1
	v_mov_b32_e32 v15, s0
	v_mov_b32_e32 v16, s1
	v_cndmask_b32_e64 v15, v15, v16, s[24:25]
	v_add_f32_e32 v14, v14, v15
	s_and_saveexec_b64 s[0:1], s[4:5]
	global_store_dword v[56:57], v14, off offset:448
	s_or_b64 exec, exec, s[0:1]
	ds_read_b128 v[18:21], v58 offset:61440
	s_waitcnt vmcnt(8)
	v_mov_b32_e32 v26, v119
	v_mov_b32_e32 v22, v110
	v_mov_b32_e32 v23, v111
	v_mov_b32_e32 v14, v92
	v_mov_b32_e32 v15, v93
	v_mov_b32_e32 v16, v94
	v_mov_b32_e32 v17, v95
	s_waitcnt lgkmcnt(0)
	v_mul_f32_e32 v27, v18, v26
	v_mul_f32_e32 v28, v19, v26
	v_mul_f32_e32 v20, v20, v26
	v_mul_f32_e32 v21, v21, v26
	s_nop 0
	v_lshlrev_b32_e32 v18, 16, v22
	v_mul_f32_e32 v26, 0xbfb8aa3b, v27
	v_and_b32_e32 v19, 0xffff0000, v22
	v_mul_f32_e32 v22, 0xbfb8aa3b, v28
	v_mul_f32_e32 v27, 0xbfb8aa3b, v20
	v_mul_f32_e32 v28, 0xbfb8aa3b, v21
	v_exp_f32_e32 v20, v26
	v_exp_f32_e32 v21, v22
	v_exp_f32_e32 v26, v27
	v_exp_f32_e32 v27, v28
	v_lshlrev_b32_e32 v22, 16, v23
	v_pk_add_f32 v[20:21], v[20:21], 1.0 op_sel_hi:[1,0]
	v_and_b32_e32 v23, 0xffff0000, v23
	v_div_scale_f32 v28, s[0:1], v21, v21, 1.0
	v_pk_add_f32 v[26:27], v[26:27], 1.0 op_sel_hi:[1,0]
	v_div_scale_f32 v30, s[0:1], v20, v20, 1.0
	v_rcp_f32_e32 v36, v28
	v_div_scale_f32 v32, s[6:7], v27, v27, 1.0
	v_rcp_f32_e32 v37, v30
	v_div_scale_f32 v34, s[8:9], v26, v26, 1.0
	v_rcp_f32_e32 v38, v32
	v_rcp_f32_e32 v39, v34
	v_fma_f32 v40, -v28, v36, 1.0
	v_div_scale_f32 v29, vcc, 1.0, v21, 1.0
	v_fma_f32 v41, -v30, v37, 1.0
	v_fmac_f32_e32 v36, v40, v36
	v_div_scale_f32 v31, s[0:1], 1.0, v20, 1.0
	v_fma_f32 v42, -v32, v38, 1.0
	v_fmac_f32_e32 v37, v41, v37
	v_mul_f32_e32 v40, v29, v36
	v_div_scale_f32 v33, s[6:7], 1.0, v27, 1.0
	v_fma_f32 v43, -v34, v39, 1.0
	v_fmac_f32_e32 v38, v42, v38
	v_mul_f32_e32 v41, v31, v37
	v_fma_f32 v44, -v28, v40, v29
	v_div_scale_f32 v35, s[8:9], 1.0, v26, 1.0
	v_fmac_f32_e32 v39, v43, v39
	v_mul_f32_e32 v42, v33, v38
	v_fma_f32 v45, -v30, v41, v31
	v_fmac_f32_e32 v40, v44, v36
	v_mul_f32_e32 v43, v35, v39
	v_fma_f32 v46, -v32, v42, v33
	v_fmac_f32_e32 v41, v45, v37
	v_fma_f32 v28, -v28, v40, v29
	v_fma_f32 v47, -v34, v43, v35
	v_fmac_f32_e32 v42, v46, v38
	v_fma_f32 v29, -v30, v41, v31
	v_div_fmas_f32 v28, v28, v36, v40
	s_mov_b64 vcc, s[0:1]
	v_fmac_f32_e32 v43, v47, v39
	v_fma_f32 v30, -v32, v42, v33
	v_div_fixup_f32 v21, v28, v21, 1.0
	v_div_fmas_f32 v28, v29, v37, v41
	s_mov_b64 vcc, s[6:7]
	v_fma_f32 v31, -v34, v43, v35
	v_div_fixup_f32 v20, v28, v20, 1.0
	v_div_fmas_f32 v28, v30, v38, v42
	s_mov_b64 vcc, s[8:9]
	s_nop 0
	v_pk_fma_f32 v[18:19], v[20:21], v[18:19], v[14:15]
	v_div_fmas_f32 v14, v31, v39, v43
	v_div_fixup_f32 v15, v28, v27, 1.0
	v_div_fixup_f32 v14, v14, v26, 1.0
	v_pk_mul_f32 v[26:27], v[18:19], v[18:19]
	v_pk_fma_f32 v[20:21], v[14:15], v[22:23], v[16:17]
	v_add_f32_e32 v16, v26, v27
	v_pk_mul_f32 v[14:15], v[20:21], v[20:21]
	global_store_dwordx4 v[50:51], v[18:21], off
	v_add_f32_e32 v14, v16, v14
	v_add_f32_e32 v14, v15, v14
	v_lshl_add_u64 v[50:51], v[50:51], 0, s[100:101]
	s_nop 0
	v_add_f32_dpp v15, v14, v14 quad_perm:[1,0,3,2] row_mask:0xf bank_mask:0xf
	s_nop 1
	v_add_f32_dpp v14, v15, v15 quad_perm:[2,3,0,1] row_mask:0xf bank_mask:0xf
	s_nop 1
	v_add_f32_dpp v15, v14, v14 row_half_mirror row_mask:0xf bank_mask:0xf
	s_nop 1
	v_add_f32_dpp v14, v15, v15 row_mirror row_mask:0xf bank_mask:0xf
	s_nop 1
	v_readlane_b32 s0, v14, 16
	v_readlane_b32 s1, v14, 48
	s_nop 1
	v_mov_b32_e32 v15, s0
	v_mov_b32_e32 v16, s1
	v_cndmask_b32_e64 v15, v15, v16, s[24:25]
	v_add_f32_e32 v14, v14, v15
	s_and_saveexec_b64 s[0:1], s[4:5]
	global_store_dword v[56:57], v14, off offset:480
	s_or_b64 exec, exec, s[0:1]
	s_branch .LBB0_1595
